# GLA prep: LDS reads of the decay dot products and the following segment pipelined 12 deep (were one read per wait)
# speedup vs baseline: 1.0159x; 1.0098x over previous
; DI int otid() { int t = threadIdx.x; asm volatile("" : "+v"(t)); return t; }
; DI void gla_prep_item(const P& p, int l, int item, unsigned char* smem) {
;     const int c = item % 72, bd = item / 72, dir = bd & 1, b = bd >> 1;
;     float* slr = (float*)smem;
;     float* stot = slr + 512;
;     float* slast = stot + 256;
;     bf16_t* sq = (bf16_t*)(slast + 256);
;     bf16_t* sk = sq + 4 * 32 * 72;
;     const bf16_t* S = (const bf16_t*)(p.ws + WS_SBUF);
;     bf16_t* QT = (bf16_t*)(p.ws + WS_GLA_QT); bf16_t* KO = (bf16_t*)(p.ws + WS_GLA_KO); bf16_t* AT = (bf16_t*)(p.ws + WS_GLA_AT); float* DC = (float*)(p.ws + WS_GLA_DC);
;     const int tid = otid();
;     { const int i = tid >> 4, r = tid & 15; slr[i * 16 + r] = ((const float*)(p.ws + WS_G))[(size_t)prow(b, dir, 32 * c + i) * NNAR + G_LR + 16 * dir + r]; }
;     __syncthreads();
;     const int cch = tid & 255, half = tid >> 8, h = cch >> 6, d = cch & 63;
;     bf16_t qraw[16], kraw[16];
; #pragma unroll
;     for (int ii = 0; ii < 16; ++ii) { const size_t row = (size_t)prow(b, dir, 32 * c + 16 * half + ii); qraw[ii] = S[row * NP + C_GLA_Q + cch]; kraw[ii] = S[row * NP + C_GLA_K + cch]; }
.LBB0_253:
	s_andn2_b64 vcc, exec, s[0:1]
	s_cbranch_vccnz .LBB0_265
	s_add_i32 s0, s28, 0xfdc0
	s_and_b32 s1, s0, 0xffff
	s_mul_i32 s1, s1, 0xe38f
	s_lshr_b32 s2, s1, 22
	s_mul_i32 s3, s2, 0x48
	s_sub_i32 s0, s0, s3
	s_and_b32 s21, s0, 0xffff
	v_mov_b32_e32 v24, v166
	s_lshl_b32 s38, s21, 5
	s_movk_i32 s0, 0xff
	v_ashrrev_i32_e32 v0, 4, v24
	v_add_u32_e32 v0, s38, v0
	s_lshr_b32 s22, s1, 23
	v_cmp_lt_i32_e32 vcc, s0, v0
	s_and_saveexec_b64 s[0:1], vcc
	s_xor_b64 s[0:1], exec, s[0:1]
	s_lshl_b32 s3, s22, 8
	s_addk_i32 s3, 0x2000
	s_lshl_b32 s20, s22, 11
	v_add_u32_e32 v1, 0xffffff00, v0
	s_or_saveexec_b64 s[0:1], s[0:1]
	v_mov_b32_e32 v3, 0x8ff
	v_mov_b32_e32 v2, s20
	v_mov_b32_e32 v4, s3
	v_mov_b32_e32 v5, s20
	s_xor_b64 exec, exec, s[0:1]
	s_lshl_b32 s4, s22, 8
	s_lshl_b32 s3, s22, 11
	s_addk_i32 s4, 0x2000
	v_mov_b32_e32 v3, 0xff
	v_mov_b32_e32 v2, s4
	v_mov_b32_e32 v5, s3
	v_mov_b32_e32 v1, v0
	v_mov_b32_e32 v4, s4
	s_or_b64 exec, exec, s[0:1]
	s_and_b32 s24, s2, 1
	s_lshl_b32 s0, s24, 6
	s_add_u32 s0, s42, s0
	s_addc_u32 s1, s43, 0
	s_add_u32 s0, s0, 0x17ead200
	s_addc_u32 s1, s1, 0
	s_cmp_eq_u32 s24, 0
	s_cselect_b64 vcc, -1, 0
	v_sub_u32_e32 v0, v3, v0
	v_cndmask_b32_e32 v0, v0, v1, vcc
	v_and_b32_e32 v25, 15, v24
	v_add_u32_e32 v2, v0, v2
	v_mov_b64_e32 v[0:1], s[0:1]
	s_movk_i32 s0, 0xc0
	v_mad_i64_i32 v[0:1], s[0:1], v2, s0, v[0:1]
	v_lshlrev_b32_e32 v132, 2, v25
	v_lshl_add_u64 v[0:1], v[0:1], 0, v[132:133]
	global_load_dword v0, v[0:1], off
	v_lshlrev_b32_e32 v43, 2, v24
	v_add_u32_e32 v1, s26, v43
	v_ashrrev_i32_e32 v37, 8, v24
	v_readlane_b32 s2, v252, 11
	v_lshlrev_b32_e32 v26, 4, v37
	s_or_b32 s2, s24, s2
	s_mov_b64 s[0:1], 0x6c3c000
	s_movk_i32 s5, 0x100
	s_ashr_i32 s3, s2, 31
	s_lshl_b64 s[2:3], s[2:3], 14
	v_readlane_b32 s48, v254, 39
	v_readlane_b32 s49, v254, 40
	s_add_u32 s36, s48, s2
	s_addc_u32 s37, s49, s3
	s_lshl_b32 s2, s24, 8
	v_readlane_b32 s3, v252, 12
	s_or_b32 s2, s2, s3
	s_movk_i32 s3, 0x3800
	v_readlane_b32 s50, v254, 41
	v_readlane_b32 s51, v254, 42
	s_mov_b32 s4, 0x7f800000
	v_readlane_b32 s52, v254, 43
	v_readlane_b32 s53, v254, 44
	v_readlane_b32 s54, v254, 45
	v_readlane_b32 s55, v254, 46
	v_readlane_b32 s56, v254, 47
	v_readlane_b32 s57, v254, 48
	v_readlane_b32 s58, v254, 49
	v_readlane_b32 s59, v254, 50
	v_readlane_b32 s60, v254, 51
	v_readlane_b32 s61, v254, 52
	v_readlane_b32 s62, v254, 53
	v_readlane_b32 s63, v254, 54
	s_waitcnt vmcnt(0)
	ds_write_b32 v1, v0
	v_and_b32_e32 v1, 0xff, v24
	v_lshlrev_b32_e32 v132, 1, v1
	v_add_u32_e32 v0, s38, v26
	v_lshl_add_u64 v[2:3], s[42:43], 0, v[132:133]
	v_lshl_add_u64 v[2:3], v[2:3], 0, s[0:1]
	v_cmp_gt_i32_e64 s[0:1], s5, v0
	v_add_u32_e32 v6, 0xffffff00, v0
	s_waitcnt lgkmcnt(0)
	v_cndmask_b32_e64 v7, v174, v175, s[0:1]
	v_cndmask_b32_e64 v6, v6, v0, s[0:1]
	v_sub_u32_e32 v7, v7, v0
	v_cndmask_b32_e64 v8, v5, v4, s[0:1]
	v_cndmask_b32_e32 v6, v7, v6, vcc
	v_add_u32_e32 v6, v8, v6
	v_mad_i64_i32 v[6:7], s[0:1], v6, s3, v[2:3]
	s_barrier
	global_load_ushort v29, v[6:7], off
	global_load_ushort v27, v[6:7], off offset:512
	v_or_b32_e32 v6, 1, v0
	v_cmp_gt_i32_e64 s[0:1], s5, v6
	v_add_u32_e32 v7, 0xffffff01, v0
	v_lshlrev_b32_e32 v132, 2, v1
	v_cndmask_b32_e64 v8, v174, v175, s[0:1]
	v_cndmask_b32_e64 v7, v7, v6, s[0:1]
	v_sub_u32_e32 v6, v8, v6
	v_cndmask_b32_e64 v9, v5, v4, s[0:1]
	v_cndmask_b32_e32 v6, v6, v7, vcc
	v_add_u32_e32 v6, v9, v6
	v_mad_i64_i32 v[6:7], s[0:1], v6, s3, v[2:3]
	global_load_ushort v30, v[6:7], off
	global_load_ushort v28, v[6:7], off offset:512
	v_or_b32_e32 v6, 2, v0
	v_cmp_gt_i32_e64 s[0:1], s5, v6
	v_add_u32_e32 v7, 0xffffff02, v0
	s_nop 0
	v_cndmask_b32_e64 v8, v174, v175, s[0:1]
	v_cndmask_b32_e64 v7, v7, v6, s[0:1]
	v_sub_u32_e32 v6, v8, v6
	v_cndmask_b32_e64 v9, v5, v4, s[0:1]
	v_cndmask_b32_e32 v6, v6, v7, vcc
	v_add_u32_e32 v6, v9, v6
	v_mad_i64_i32 v[6:7], s[0:1], v6, s3, v[2:3]
	global_load_ushort v32, v[6:7], off
	global_load_ushort v31, v[6:7], off offset:512
	v_or_b32_e32 v6, 3, v0
	v_cmp_gt_i32_e64 s[0:1], s5, v6
	v_add_u32_e32 v7, 0xffffff03, v0
	s_nop 0
	v_cndmask_b32_e64 v8, v174, v175, s[0:1]
	v_cndmask_b32_e64 v7, v7, v6, s[0:1]
	v_sub_u32_e32 v6, v8, v6
	v_cndmask_b32_e64 v9, v5, v4, s[0:1]
	v_cndmask_b32_e32 v6, v6, v7, vcc
	v_add_u32_e32 v6, v9, v6
	v_mad_i64_i32 v[6:7], s[0:1], v6, s3, v[2:3]
	global_load_ushort v34, v[6:7], off
	global_load_ushort v33, v[6:7], off offset:512
	v_or_b32_e32 v6, 4, v0
	v_cmp_gt_i32_e64 s[0:1], s5, v6
	v_add_u32_e32 v7, 0xffffff04, v0
	s_nop 0
	v_cndmask_b32_e64 v8, v174, v175, s[0:1]
	v_cndmask_b32_e64 v7, v7, v6, s[0:1]
	v_sub_u32_e32 v6, v8, v6
	v_cndmask_b32_e64 v9, v5, v4, s[0:1]
	v_cndmask_b32_e32 v6, v6, v7, vcc
	v_add_u32_e32 v6, v9, v6
	v_mad_i64_i32 v[6:7], s[0:1], v6, s3, v[2:3]
	global_load_ushort v60, v[6:7], off
	global_load_ushort v59, v[6:7], off offset:512
	v_or_b32_e32 v6, 5, v0
	v_cmp_gt_i32_e64 s[0:1], s5, v6
	v_add_u32_e32 v7, 0xffffff05, v0
	s_nop 0
	v_cndmask_b32_e64 v8, v174, v175, s[0:1]
	v_cndmask_b32_e64 v7, v7, v6, s[0:1]
	v_sub_u32_e32 v6, v8, v6
	v_cndmask_b32_e64 v9, v5, v4, s[0:1]
	v_cndmask_b32_e32 v6, v6, v7, vcc
	v_add_u32_e32 v6, v9, v6
	v_mad_i64_i32 v[6:7], s[0:1], v6, s3, v[2:3]
	global_load_ushort v58, v[6:7], off
	global_load_ushort v56, v[6:7], off offset:512
	v_or_b32_e32 v6, 6, v0
	v_cmp_gt_i32_e64 s[0:1], s5, v6
	v_add_u32_e32 v7, 0xffffff06, v0
	s_nop 0
	v_cndmask_b32_e64 v8, v174, v175, s[0:1]
	v_cndmask_b32_e64 v7, v7, v6, s[0:1]
	v_sub_u32_e32 v6, v8, v6
	v_cndmask_b32_e64 v9, v5, v4, s[0:1]
	v_cndmask_b32_e32 v6, v6, v7, vcc
	v_add_u32_e32 v6, v9, v6
	v_mad_i64_i32 v[6:7], s[0:1], v6, s3, v[2:3]
	global_load_ushort v55, v[6:7], off
; DI void gla_prep_item(const P& p, int l, int item, unsigned char* smem) {
;     ...
;     for (int ii = 0; ii < 16; ++ii) { const size_t row = (size_t)prow(b, dir, 32 * c + 16 * half + ii); qraw[ii] = S[row * NP + C_GLA_Q + cch]; kraw[ii] = S[row * NP + C_GLA_K + cch]; }
;     float wd[16];
; #pragma unroll
;     for (int r = 0; r < 16; ++r) wd[r] = p.gla_wd[((size_t)(l * 2 + dir) * 16 + r) * 256 + cch];
;     const float bdv = p.gla_bd[(l * 2 + dir) * 256 + cch];
;     float cum[16]; float run = 0.f;
; #pragma unroll
;     for (int ii = 0; ii < 16; ++ii) {
;         const int i = 16 * half + ii; float z = bdv;
; #pragma unroll
;         for (int r = 0; r < 16; ++r) z += slr[i * 16 + r] * wd[r];
;         const float ls = fminf(z, 0.f) - __logf(1.f + __expf(-fabsf(z)));
	global_load_ushort v53, v[6:7], off offset:512
	v_or_b32_e32 v6, 7, v0
	v_cmp_gt_i32_e64 s[0:1], s5, v6
	v_add_u32_e32 v7, 0xffffff07, v0
	s_nop 0
	v_cndmask_b32_e64 v8, v174, v175, s[0:1]
	v_cndmask_b32_e64 v7, v7, v6, s[0:1]
	v_sub_u32_e32 v6, v8, v6
	v_cndmask_b32_e64 v9, v5, v4, s[0:1]
	v_cndmask_b32_e32 v6, v6, v7, vcc
	v_add_u32_e32 v6, v9, v6
	v_mad_i64_i32 v[6:7], s[0:1], v6, s3, v[2:3]
	global_load_ushort v57, v[6:7], off
	global_load_ushort v54, v[6:7], off offset:512
	v_or_b32_e32 v6, 8, v0
	v_cmp_gt_i32_e64 s[0:1], s5, v6
	v_add_u32_e32 v7, 0xffffff08, v0
	s_nop 0
	v_cndmask_b32_e64 v8, v174, v175, s[0:1]
	v_cndmask_b32_e64 v7, v7, v6, s[0:1]
	v_sub_u32_e32 v6, v8, v6
	v_cndmask_b32_e64 v9, v5, v4, s[0:1]
	v_cndmask_b32_e32 v6, v6, v7, vcc
	v_add_u32_e32 v6, v9, v6
	v_mad_i64_i32 v[6:7], s[0:1], v6, s3, v[2:3]
	global_load_ushort v52, v[6:7], off
	global_load_ushort v51, v[6:7], off offset:512
	v_or_b32_e32 v6, 9, v0
	v_cmp_gt_i32_e64 s[0:1], s5, v6
	v_add_u32_e32 v7, 0xffffff09, v0
	s_nop 0
	v_cndmask_b32_e64 v8, v174, v175, s[0:1]
	v_cndmask_b32_e64 v7, v7, v6, s[0:1]
	v_sub_u32_e32 v6, v8, v6
	v_cndmask_b32_e64 v9, v5, v4, s[0:1]
	v_cndmask_b32_e32 v6, v6, v7, vcc
	v_add_u32_e32 v6, v9, v6
	v_mad_i64_i32 v[6:7], s[0:1], v6, s3, v[2:3]
	global_load_ushort v50, v[6:7], off
	global_load_ushort v49, v[6:7], off offset:512
	v_or_b32_e32 v6, 10, v0
	v_cmp_gt_i32_e64 s[0:1], s5, v6
	v_add_u32_e32 v7, 0xffffff0a, v0
	s_nop 0
	v_cndmask_b32_e64 v8, v174, v175, s[0:1]
	v_cndmask_b32_e64 v7, v7, v6, s[0:1]
	v_sub_u32_e32 v6, v8, v6
	v_cndmask_b32_e64 v9, v5, v4, s[0:1]
	v_cndmask_b32_e32 v6, v6, v7, vcc
	v_add_u32_e32 v6, v9, v6
	v_mad_i64_i32 v[6:7], s[0:1], v6, s3, v[2:3]
	global_load_ushort v48, v[6:7], off
	global_load_ushort v47, v[6:7], off offset:512
	v_or_b32_e32 v6, 11, v0
	v_cmp_gt_i32_e64 s[0:1], s5, v6
	v_add_u32_e32 v7, 0xffffff0b, v0
	s_nop 0
	v_cndmask_b32_e64 v8, v174, v175, s[0:1]
	v_cndmask_b32_e64 v7, v7, v6, s[0:1]
	v_sub_u32_e32 v6, v8, v6
	v_cndmask_b32_e64 v9, v5, v4, s[0:1]
	v_cndmask_b32_e32 v6, v6, v7, vcc
	v_add_u32_e32 v6, v9, v6
	v_mad_i64_i32 v[6:7], s[0:1], v6, s3, v[2:3]
	global_load_ushort v46, v[6:7], off
	global_load_ushort v45, v[6:7], off offset:512
	v_or_b32_e32 v6, 12, v0
	v_cmp_gt_i32_e64 s[0:1], s5, v6
	v_add_u32_e32 v7, 0xffffff0c, v0
	s_nop 0
	v_cndmask_b32_e64 v8, v174, v175, s[0:1]
	v_cndmask_b32_e64 v7, v7, v6, s[0:1]
	v_sub_u32_e32 v6, v8, v6
	v_cndmask_b32_e64 v9, v5, v4, s[0:1]
	v_cndmask_b32_e32 v6, v6, v7, vcc
	v_add_u32_e32 v6, v9, v6
	v_mad_i64_i32 v[6:7], s[0:1], v6, s3, v[2:3]
	global_load_ushort v44, v[6:7], off
	global_load_ushort v42, v[6:7], off offset:512
	v_or_b32_e32 v6, 13, v0
	v_cmp_gt_i32_e64 s[0:1], s5, v6
	v_add_u32_e32 v7, 0xffffff0d, v0
	s_nop 0
	v_cndmask_b32_e64 v8, v174, v175, s[0:1]
	v_cndmask_b32_e64 v7, v7, v6, s[0:1]
	v_sub_u32_e32 v6, v8, v6
	v_cndmask_b32_e64 v9, v5, v4, s[0:1]
	v_cndmask_b32_e32 v6, v6, v7, vcc
	v_add_u32_e32 v6, v9, v6
	v_mad_i64_i32 v[6:7], s[0:1], v6, s3, v[2:3]
	global_load_ushort v41, v[6:7], off
	global_load_ushort v40, v[6:7], off offset:512
	v_or_b32_e32 v6, 14, v0
	v_cmp_gt_i32_e64 s[0:1], s5, v6
	v_add_u32_e32 v7, 0xffffff0e, v0
	s_nop 0
	v_cndmask_b32_e64 v8, v174, v175, s[0:1]
	v_cndmask_b32_e64 v7, v7, v6, s[0:1]
	v_sub_u32_e32 v6, v8, v6
	v_cndmask_b32_e64 v9, v5, v4, s[0:1]
	v_cndmask_b32_e32 v6, v6, v7, vcc
	v_add_u32_e32 v6, v9, v6
	v_mad_i64_i32 v[6:7], s[0:1], v6, s3, v[2:3]
	global_load_ushort v39, v[6:7], off
	global_load_ushort v38, v[6:7], off offset:512
	v_or_b32_e32 v6, 15, v0
	v_cmp_gt_i32_e64 s[0:1], s5, v6
	v_add_u32_e32 v7, 0xffffff0f, v0
	s_nop 0
	v_cndmask_b32_e64 v8, v174, v175, s[0:1]
	v_cndmask_b32_e64 v7, v7, v6, s[0:1]
	v_cndmask_b32_e64 v4, v5, v4, s[0:1]
	v_sub_u32_e32 v5, v8, v6
	v_cndmask_b32_e32 v5, v5, v7, vcc
	v_add_u32_e32 v4, v4, v5
	v_mad_i64_i32 v[2:3], s[0:1], v4, s3, v[2:3]
	global_load_ushort v36, v[2:3], off
	global_load_ushort v35, v[2:3], off offset:512
	v_lshl_add_u64 v[2:3], s[36:37], 0, v[132:133]
	s_movk_i32 s0, 0x1000
	v_add_co_u32_e32 v4, vcc, s0, v2
	s_movk_i32 s0, 0x3000
	s_nop 0
	v_addc_co_u32_e32 v5, vcc, 0, v3, vcc
	s_nop 1
	v_add_co_u32_e32 v10, vcc, s33, v2
	global_load_dword v67, v132, s[36:37]
	global_load_dword v68, v132, s[36:37] offset:1024
	global_load_dword v63, v132, s[36:37] offset:2048
	global_load_dword v64, v132, s[36:37] offset:3072
	v_addc_co_u32_e32 v11, vcc, 0, v3, vcc
	global_load_dword v65, v[10:11], off offset:-4096
	global_load_dword v66, v[4:5], off offset:1024
	global_load_dword v61, v[4:5], off offset:2048
	global_load_dword v62, v[4:5], off offset:3072
	global_load_dword v8, v[10:11], off
	global_load_dword v9, v[10:11], off offset:1024
	global_load_dword v6, v[10:11], off offset:2048
	global_load_dword v7, v[10:11], off offset:3072
	v_add_co_u32_e32 v10, vcc, s0, v2
	s_mov_b32 s3, 0x3f317217
	s_nop 0
	v_addc_co_u32_e32 v11, vcc, 0, v3, vcc
	global_load_dword v4, v[10:11], off
	global_load_dword v5, v[10:11], off offset:1024
	global_load_dword v2, v[10:11], off offset:2048
	global_load_dword v3, v[10:11], off offset:3072
	v_or_b32_e32 v10, s2, v1
	v_ashrrev_i32_e32 v11, 31, v10
	v_lshl_add_u64 v[10:11], v[10:11], 2, s[50:51]
	global_load_dword v69, v[10:11], off
	v_and_b32_e32 v10, 0x3fffff00, v24
	v_lshl_add_u32 v70, v10, 2, s26
	ds_read2_b32 v[74:75], v70 offset1:1
	ds_read2_b32 v[76:77], v70 offset0:2 offset1:3
	ds_read2_b32 v[78:79], v70 offset0:4 offset1:5
	ds_read2_b32 v[80:81], v70 offset0:6 offset1:7
	ds_read2_b32 v[82:83], v70 offset0:8 offset1:9
	ds_read2_b32 v[84:85], v70 offset0:10 offset1:11
	ds_read2_b32 v[86:87], v70 offset0:12 offset1:13
	ds_read2_b32 v[88:89], v70 offset0:14 offset1:15
	ds_read2_b32 v[90:91], v70 offset0:16 offset1:17
	ds_read2_b32 v[92:93], v70 offset0:18 offset1:19
	ds_read2_b32 v[94:95], v70 offset0:20 offset1:21
	ds_read2_b32 v[96:97], v70 offset0:22 offset1:23
	s_mov_b32 s2, 0xbfb8aa3b
	s_waitcnt vmcnt(0)
; DI void gla_prep_item(const P& p, int l, int item, unsigned char* smem) {
;     ...
;     for (int ii = 0; ii < 16; ++ii) {
;         const int i = 16 * half + ii; float z = bdv;
; #pragma unroll
;         for (int r = 0; r < 16; ++r) z += slr[i * 16 + r] * wd[r];
;         const float ls = fminf(z, 0.f) - __logf(1.f + __expf(-fabsf(z)));
;         run += ls * (1.f / 16.f); cum[ii] = run;
;     }
	s_waitcnt lgkmcnt(11)
	v_fma_f32 v12, v67, v74, v69
	ds_read2_b32 v[98:99], v70 offset0:24 offset1:25
	v_fmac_f32_e32 v12, v68, v75
	s_waitcnt lgkmcnt(11)
	v_fmac_f32_e32 v12, v63, v76
	ds_read2_b32 v[100:101], v70 offset0:26 offset1:27
	v_fmac_f32_e32 v12, v64, v77
	s_waitcnt lgkmcnt(11)
	v_fmac_f32_e32 v12, v65, v78
	ds_read2_b32 v[102:103], v70 offset0:28 offset1:29
	v_fmac_f32_e32 v12, v66, v79
	s_waitcnt lgkmcnt(11)
	v_fmac_f32_e32 v12, v61, v80
	ds_read2_b32 v[104:105], v70 offset0:30 offset1:31
	v_fmac_f32_e32 v12, v62, v81
	s_waitcnt lgkmcnt(11)
	v_pk_mul_f32 v[10:11], v[8:9], v[82:83]
	ds_read2_b32 v[106:107], v70 offset0:32 offset1:33
	s_nop 0
	v_add_f32_e32 v10, v12, v10
	v_add_f32_e32 v12, v10, v11
	s_waitcnt lgkmcnt(11)
	v_pk_mul_f32 v[10:11], v[6:7], v[84:85]
	ds_read2_b32 v[108:109], v70 offset0:34 offset1:35
	s_nop 0
	v_add_f32_e32 v10, v12, v10
	v_add_f32_e32 v12, v10, v11
	s_waitcnt lgkmcnt(11)
	v_pk_mul_f32 v[10:11], v[4:5], v[86:87]
	ds_read2_b32 v[112:113], v70 offset0:36 offset1:37
	s_nop 0
	v_add_f32_e32 v10, v12, v10
	v_add_f32_e32 v12, v10, v11
	s_waitcnt lgkmcnt(11)
	v_pk_mul_f32 v[10:11], v[2:3], v[88:89]
	ds_read2_b32 v[114:115], v70 offset0:38 offset1:39
	s_nop 0
	v_add_f32_e32 v10, v12, v10
	v_add_f32_e32 v10, v10, v11
	v_min_f32_e32 v11, 0, v10
	v_mul_f32_e64 v10, |v10|, s2
	v_exp_f32_e32 v10, v10
	s_nop 0
	v_add_f32_e32 v10, 1.0, v10
	v_cmp_gt_f32_e32 vcc, s23, v10
	s_nop 1
	v_cndmask_b32_e64 v12, 0, 32, vcc
	v_ldexp_f32 v10, v10, v12
	v_log_f32_e32 v10, v10
	s_nop 0
	v_mul_f32_e32 v12, 0x3f317217, v10
	v_fma_f32 v12, v10, s3, -v12
	v_fmac_f32_e32 v12, 0x3377d1cf, v10
	v_fmac_f32_e32 v12, 0x3f317217, v10
	v_cmp_lt_f32_e64 s[0:1], |v10|, s4
	s_nop 1
	v_cndmask_b32_e64 v10, v10, v12, s[0:1]
	v_cndmask_b32_e32 v12, 0, v176, vcc
	v_sub_f32_e32 v10, v10, v12
	v_sub_f32_e32 v12, v11, v10
	s_waitcnt lgkmcnt(11)
	v_fma_f32 v13, v67, v90, v69
	ds_read2_b32 v[116:117], v70 offset0:40 offset1:41
	v_fmac_f32_e32 v13, v68, v91
	s_waitcnt lgkmcnt(11)
	v_fmac_f32_e32 v13, v63, v92
	ds_read2_b32 v[118:119], v70 offset0:42 offset1:43
	v_fmac_f32_e32 v13, v64, v93
	s_waitcnt lgkmcnt(11)
	v_fmac_f32_e32 v13, v65, v94
	ds_read2_b32 v[120:121], v70 offset0:44 offset1:45
	v_fmac_f32_e32 v13, v66, v95
	s_waitcnt lgkmcnt(11)
	v_fmac_f32_e32 v13, v61, v96
	ds_read2_b32 v[122:123], v70 offset0:46 offset1:47
	v_fmac_f32_e32 v13, v62, v97
	s_waitcnt lgkmcnt(11)
	v_pk_mul_f32 v[10:11], v[8:9], v[98:99]
	ds_read2_b32 v[124:125], v70 offset0:48 offset1:49
	s_nop 0
	v_add_f32_e32 v10, v13, v10
	v_add_f32_e32 v13, v10, v11
	s_waitcnt lgkmcnt(11)
	v_pk_mul_f32 v[10:11], v[6:7], v[100:101]
	ds_read2_b32 v[126:127], v70 offset0:50 offset1:51
	s_nop 0
	v_add_f32_e32 v10, v13, v10
	v_add_f32_e32 v13, v10, v11
	s_waitcnt lgkmcnt(11)
	v_pk_mul_f32 v[10:11], v[4:5], v[102:103]
	ds_read2_b32 v[142:143], v70 offset0:52 offset1:53
	s_nop 0
	v_add_f32_e32 v10, v13, v10
	v_add_f32_e32 v13, v10, v11
	s_waitcnt lgkmcnt(11)
	v_pk_mul_f32 v[10:11], v[2:3], v[104:105]
	ds_read2_b32 v[144:145], v70 offset0:54 offset1:55
	s_nop 0
	v_add_f32_e32 v10, v13, v10
	v_add_f32_e32 v10, v10, v11
	v_min_f32_e32 v11, 0, v10
	v_mul_f32_e64 v10, |v10|, s2
	v_exp_f32_e32 v10, v10
	s_nop 0
	v_add_f32_e32 v10, 1.0, v10
	v_cmp_gt_f32_e32 vcc, s23, v10
	s_nop 1
	v_cndmask_b32_e64 v13, 0, 32, vcc
	v_ldexp_f32 v10, v10, v13
	v_log_f32_e32 v10, v10
	s_nop 0
	v_mul_f32_e32 v13, 0x3f317217, v10
	v_fma_f32 v13, v10, s3, -v13
	v_fmac_f32_e32 v13, 0x3377d1cf, v10
	v_fmac_f32_e32 v13, 0x3f317217, v10
	v_cmp_lt_f32_e64 s[0:1], |v10|, s4
	s_nop 1
	v_cndmask_b32_e64 v10, v10, v13, s[0:1]
	v_cndmask_b32_e32 v13, 0, v176, vcc
	v_sub_f32_e32 v10, v10, v13
	s_mov_b32 s0, 0x3d800000
	v_sub_f32_e32 v11, v11, v10
	v_fma_f32 v10, v12, s0, 0
	v_fmamk_f32 v11, v11, 0x3d800000, v10
	s_waitcnt lgkmcnt(11)
	v_fma_f32 v14, v67, v106, v69
	ds_read2_b32 v[146:147], v70 offset0:56 offset1:57
	v_fmac_f32_e32 v14, v68, v107
	s_waitcnt lgkmcnt(11)
	v_fmac_f32_e32 v14, v63, v108
	ds_read2_b32 v[148:149], v70 offset0:58 offset1:59
	v_fmac_f32_e32 v14, v64, v109
	s_waitcnt lgkmcnt(11)
	v_fmac_f32_e32 v14, v65, v112
	ds_read2_b32 v[150:151], v70 offset0:60 offset1:61
	v_fmac_f32_e32 v14, v66, v113
	s_waitcnt lgkmcnt(11)
	v_fmac_f32_e32 v14, v61, v114
	ds_read2_b32 v[152:153], v70 offset0:62 offset1:63
	v_fmac_f32_e32 v14, v62, v115
	s_waitcnt lgkmcnt(11)
	v_pk_mul_f32 v[12:13], v[8:9], v[116:117]
	ds_read2_b32 v[154:155], v70 offset0:64 offset1:65
	s_nop 0
	v_add_f32_e32 v12, v14, v12
	v_add_f32_e32 v14, v12, v13
	s_waitcnt lgkmcnt(11)
	v_pk_mul_f32 v[12:13], v[6:7], v[118:119]
	ds_read2_b32 v[156:157], v70 offset0:66 offset1:67
	s_nop 0
	v_add_f32_e32 v12, v14, v12
	v_add_f32_e32 v14, v12, v13
	s_waitcnt lgkmcnt(11)
	v_pk_mul_f32 v[12:13], v[4:5], v[120:121]
	ds_read2_b32 v[158:159], v70 offset0:68 offset1:69
	s_nop 0
	v_add_f32_e32 v12, v14, v12
	v_add_f32_e32 v14, v12, v13
	s_waitcnt lgkmcnt(11)
	v_pk_mul_f32 v[12:13], v[2:3], v[122:123]
	ds_read2_b32 v[160:161], v70 offset0:70 offset1:71
	s_nop 0
	v_add_f32_e32 v12, v14, v12
	v_add_f32_e32 v12, v12, v13
	v_min_f32_e32 v13, 0, v12
	v_mul_f32_e64 v12, |v12|, s2
	v_exp_f32_e32 v12, v12
	s_nop 0
	v_add_f32_e32 v12, 1.0, v12
	v_cmp_gt_f32_e32 vcc, s23, v12
	s_nop 1
	v_cndmask_b32_e64 v14, 0, 32, vcc
	v_ldexp_f32 v12, v12, v14
	v_log_f32_e32 v12, v12
	s_nop 0
	v_mul_f32_e32 v14, 0x3f317217, v12
	v_fma_f32 v14, v12, s3, -v14
	v_fmac_f32_e32 v14, 0x3377d1cf, v12
	v_fmac_f32_e32 v14, 0x3f317217, v12
	v_cmp_lt_f32_e64 s[0:1], |v12|, s4
	s_nop 1
	v_cndmask_b32_e64 v12, v12, v14, s[0:1]
	v_cndmask_b32_e32 v14, 0, v176, vcc
	v_sub_f32_e32 v12, v12, v14
	v_sub_f32_e32 v14, v13, v12
	s_waitcnt lgkmcnt(11)
; DI void gla_prep_item(const P& p, int l, int item, unsigned char* smem) {
;     ...
;     for (int ii = 0; ii < 16; ++ii) {
;         const int i = 16 * half + ii; float z = bdv;
; #pragma unroll
;         for (int r = 0; r < 16; ++r) z += slr[i * 16 + r] * wd[r];
;         const float ls = fminf(z, 0.f) - __logf(1.f + __expf(-fabsf(z)));
;         run += ls * (1.f / 16.f); cum[ii] = run;
;     }
	v_fma_f32 v15, v67, v124, v69
	ds_read2_b32 v[162:163], v70 offset0:72 offset1:73
	v_fmac_f32_e32 v15, v68, v125
	s_waitcnt lgkmcnt(11)
	v_fmac_f32_e32 v15, v63, v126
	ds_read2_b32 v[164:165], v70 offset0:74 offset1:75
	v_fmac_f32_e32 v15, v64, v127
	s_waitcnt lgkmcnt(11)
	v_fmac_f32_e32 v15, v65, v142
	ds_read2_b32 v[184:185], v70 offset0:76 offset1:77
	v_fmac_f32_e32 v15, v66, v143
	s_waitcnt lgkmcnt(11)
	v_fmac_f32_e32 v15, v61, v144
	ds_read2_b32 v[186:187], v70 offset0:78 offset1:79
	v_fmac_f32_e32 v15, v62, v145
	s_waitcnt lgkmcnt(11)
	v_pk_mul_f32 v[12:13], v[8:9], v[146:147]
	ds_read2_b32 v[188:189], v70 offset0:80 offset1:81
	s_nop 0
	v_add_f32_e32 v12, v15, v12
	v_add_f32_e32 v15, v12, v13
	s_waitcnt lgkmcnt(11)
	v_pk_mul_f32 v[12:13], v[6:7], v[148:149]
	ds_read2_b32 v[190:191], v70 offset0:82 offset1:83
	s_nop 0
	v_add_f32_e32 v12, v15, v12
	v_add_f32_e32 v15, v12, v13
	s_waitcnt lgkmcnt(11)
	v_pk_mul_f32 v[12:13], v[4:5], v[150:151]
	ds_read2_b32 v[192:193], v70 offset0:84 offset1:85
	s_nop 0
	v_add_f32_e32 v12, v15, v12
	v_add_f32_e32 v15, v12, v13
	s_waitcnt lgkmcnt(11)
	v_pk_mul_f32 v[12:13], v[2:3], v[152:153]
	ds_read2_b32 v[194:195], v70 offset0:86 offset1:87
	s_nop 0
	v_add_f32_e32 v12, v15, v12
	v_add_f32_e32 v12, v12, v13
	v_min_f32_e32 v13, 0, v12
	v_mul_f32_e64 v12, |v12|, s2
	v_exp_f32_e32 v12, v12
	s_nop 0
	v_add_f32_e32 v12, 1.0, v12
	v_cmp_gt_f32_e32 vcc, s23, v12
	s_nop 1
	v_cndmask_b32_e64 v15, 0, 32, vcc
	v_ldexp_f32 v12, v12, v15
	v_log_f32_e32 v12, v12
	s_nop 0
	v_mul_f32_e32 v15, 0x3f317217, v12
	v_fma_f32 v15, v12, s3, -v15
	v_fmac_f32_e32 v15, 0x3377d1cf, v12
	v_fmac_f32_e32 v15, 0x3f317217, v12
	v_cmp_lt_f32_e64 s[0:1], |v12|, s4
	s_nop 1
	v_cndmask_b32_e64 v12, v12, v15, s[0:1]
	v_cndmask_b32_e32 v15, 0, v176, vcc
	v_sub_f32_e32 v12, v12, v15
	v_sub_f32_e32 v13, v13, v12
	v_fmamk_f32 v12, v14, 0x3d800000, v11
	v_fmamk_f32 v13, v13, 0x3d800000, v12
	s_waitcnt lgkmcnt(11)
	v_fma_f32 v16, v67, v154, v69
	ds_read2_b32 v[196:197], v70 offset0:88 offset1:89
	v_fmac_f32_e32 v16, v68, v155
	s_waitcnt lgkmcnt(11)
	v_fmac_f32_e32 v16, v63, v156
	ds_read2_b32 v[198:199], v70 offset0:90 offset1:91
	v_fmac_f32_e32 v16, v64, v157
	s_waitcnt lgkmcnt(11)
	v_fmac_f32_e32 v16, v65, v158
	ds_read2_b32 v[200:201], v70 offset0:92 offset1:93
	v_fmac_f32_e32 v16, v66, v159
	s_waitcnt lgkmcnt(11)
	v_fmac_f32_e32 v16, v61, v160
	ds_read2_b32 v[202:203], v70 offset0:94 offset1:95
	v_fmac_f32_e32 v16, v62, v161
	s_waitcnt lgkmcnt(11)
	v_pk_mul_f32 v[14:15], v[8:9], v[162:163]
	ds_read2_b32 v[204:205], v70 offset0:96 offset1:97
	s_nop 0
	v_add_f32_e32 v14, v16, v14
	v_add_f32_e32 v16, v14, v15
	s_waitcnt lgkmcnt(11)
	v_pk_mul_f32 v[14:15], v[6:7], v[164:165]
	ds_read2_b32 v[206:207], v70 offset0:98 offset1:99
	s_nop 0
	v_add_f32_e32 v14, v16, v14
	v_add_f32_e32 v16, v14, v15
	s_waitcnt lgkmcnt(11)
	v_pk_mul_f32 v[14:15], v[4:5], v[184:185]
	ds_read2_b32 v[208:209], v70 offset0:100 offset1:101
	s_nop 0
	v_add_f32_e32 v14, v16, v14
	v_add_f32_e32 v16, v14, v15
	s_waitcnt lgkmcnt(11)
	v_pk_mul_f32 v[14:15], v[2:3], v[186:187]
	ds_read2_b32 v[210:211], v70 offset0:102 offset1:103
	s_nop 0
	v_add_f32_e32 v14, v16, v14
	v_add_f32_e32 v14, v14, v15
	v_min_f32_e32 v15, 0, v14
	v_mul_f32_e64 v14, |v14|, s2
	v_exp_f32_e32 v14, v14
	s_nop 0
	v_add_f32_e32 v14, 1.0, v14
	v_cmp_gt_f32_e32 vcc, s23, v14
	s_nop 1
	v_cndmask_b32_e64 v16, 0, 32, vcc
	v_ldexp_f32 v14, v14, v16
	v_log_f32_e32 v14, v14
	s_nop 0
	v_mul_f32_e32 v16, 0x3f317217, v14
	v_fma_f32 v16, v14, s3, -v16
	v_fmac_f32_e32 v16, 0x3377d1cf, v14
	v_fmac_f32_e32 v16, 0x3f317217, v14
	v_cmp_lt_f32_e64 s[0:1], |v14|, s4
	s_nop 1
	v_cndmask_b32_e64 v14, v14, v16, s[0:1]
	v_cndmask_b32_e32 v16, 0, v176, vcc
	v_sub_f32_e32 v14, v14, v16
	v_sub_f32_e32 v16, v15, v14
	s_waitcnt lgkmcnt(11)
	v_fma_f32 v17, v67, v188, v69
	ds_read2_b32 v[212:213], v70 offset0:104 offset1:105
	v_fmac_f32_e32 v17, v68, v189
	s_waitcnt lgkmcnt(11)
	v_fmac_f32_e32 v17, v63, v190
	ds_read2_b32 v[214:215], v70 offset0:106 offset1:107
	v_fmac_f32_e32 v17, v64, v191
	s_waitcnt lgkmcnt(11)
	v_fmac_f32_e32 v17, v65, v192
	ds_read2_b32 v[216:217], v70 offset0:108 offset1:109
	v_fmac_f32_e32 v17, v66, v193
	s_waitcnt lgkmcnt(11)
	v_fmac_f32_e32 v17, v61, v194
	ds_read2_b32 v[218:219], v70 offset0:110 offset1:111
	v_fmac_f32_e32 v17, v62, v195
	s_waitcnt lgkmcnt(11)
	v_pk_mul_f32 v[14:15], v[8:9], v[196:197]
	ds_read2_b32 v[224:225], v70 offset0:112 offset1:113
	s_nop 0
	v_add_f32_e32 v14, v17, v14
	v_add_f32_e32 v17, v14, v15
	s_waitcnt lgkmcnt(11)
	v_pk_mul_f32 v[14:15], v[6:7], v[198:199]
	ds_read2_b32 v[226:227], v70 offset0:114 offset1:115
	s_nop 0
	v_add_f32_e32 v14, v17, v14
	v_add_f32_e32 v17, v14, v15
	s_waitcnt lgkmcnt(11)
	v_pk_mul_f32 v[14:15], v[4:5], v[200:201]
	ds_read2_b32 v[228:229], v70 offset0:116 offset1:117
	s_nop 0
	v_add_f32_e32 v14, v17, v14
	v_add_f32_e32 v17, v14, v15
	s_waitcnt lgkmcnt(11)
	v_pk_mul_f32 v[14:15], v[2:3], v[202:203]
	ds_read2_b32 v[230:231], v70 offset0:118 offset1:119
	s_nop 0
	v_add_f32_e32 v14, v17, v14
	v_add_f32_e32 v14, v14, v15
	v_min_f32_e32 v15, 0, v14
	v_mul_f32_e64 v14, |v14|, s2
	v_exp_f32_e32 v14, v14
	s_nop 0
	v_add_f32_e32 v14, 1.0, v14
	v_cmp_gt_f32_e32 vcc, s23, v14
	s_nop 1
	v_cndmask_b32_e64 v17, 0, 32, vcc
	v_ldexp_f32 v14, v14, v17
	v_log_f32_e32 v14, v14
	s_nop 0
	v_mul_f32_e32 v17, 0x3f317217, v14
	v_fma_f32 v17, v14, s3, -v17
	v_fmac_f32_e32 v17, 0x3377d1cf, v14
	v_fmac_f32_e32 v17, 0x3f317217, v14
	v_cmp_lt_f32_e64 s[0:1], |v14|, s4
	s_nop 1
	v_cndmask_b32_e64 v14, v14, v17, s[0:1]
	v_cndmask_b32_e32 v17, 0, v176, vcc
	v_sub_f32_e32 v14, v14, v17
	v_sub_f32_e32 v15, v15, v14
	v_fmamk_f32 v14, v16, 0x3d800000, v13
	v_fmamk_f32 v15, v15, 0x3d800000, v14
	s_waitcnt lgkmcnt(11)
; DI void gla_prep_item(const P& p, int l, int item, unsigned char* smem) {
;     ...
;     for (int ii = 0; ii < 16; ++ii) {
;         const int i = 16 * half + ii; float z = bdv;
; #pragma unroll
;         for (int r = 0; r < 16; ++r) z += slr[i * 16 + r] * wd[r];
;         const float ls = fminf(z, 0.f) - __logf(1.f + __expf(-fabsf(z)));
;         run += ls * (1.f / 16.f); cum[ii] = run;
;     }
	v_fma_f32 v18, v67, v204, v69
	ds_read2_b32 v[232:233], v70 offset0:120 offset1:121
	v_fmac_f32_e32 v18, v68, v205
	s_waitcnt lgkmcnt(11)
	v_fmac_f32_e32 v18, v63, v206
	ds_read2_b32 v[234:235], v70 offset0:122 offset1:123
	v_fmac_f32_e32 v18, v64, v207
	s_waitcnt lgkmcnt(11)
	v_fmac_f32_e32 v18, v65, v208
	ds_read2_b32 v[236:237], v70 offset0:124 offset1:125
	v_fmac_f32_e32 v18, v66, v209
	s_waitcnt lgkmcnt(11)
	v_fmac_f32_e32 v18, v61, v210
	ds_read2_b32 v[238:239], v70 offset0:126 offset1:127
	v_fmac_f32_e32 v18, v62, v211
	s_waitcnt lgkmcnt(11)
	v_pk_mul_f32 v[16:17], v[8:9], v[212:213]
	ds_read2_b32 v[240:241], v70 offset0:128 offset1:129
	s_nop 0
	v_add_f32_e32 v16, v18, v16
	v_add_f32_e32 v18, v16, v17
	s_waitcnt lgkmcnt(11)
	v_pk_mul_f32 v[16:17], v[6:7], v[214:215]
	ds_read2_b32 v[242:243], v70 offset0:130 offset1:131
	s_nop 0
	v_add_f32_e32 v16, v18, v16
	v_add_f32_e32 v18, v16, v17
	s_waitcnt lgkmcnt(11)
	v_pk_mul_f32 v[16:17], v[4:5], v[216:217]
	ds_read2_b32 v[244:245], v70 offset0:132 offset1:133
	s_nop 0
	v_add_f32_e32 v16, v18, v16
	v_add_f32_e32 v18, v16, v17
	s_waitcnt lgkmcnt(11)
	v_pk_mul_f32 v[16:17], v[2:3], v[218:219]
	ds_read2_b32 v[246:247], v70 offset0:134 offset1:135
	s_nop 0
	v_add_f32_e32 v16, v18, v16
	v_add_f32_e32 v16, v16, v17
	v_min_f32_e32 v17, 0, v16
	v_mul_f32_e64 v16, |v16|, s2
	v_exp_f32_e32 v16, v16
	s_nop 0
	v_add_f32_e32 v16, 1.0, v16
	v_cmp_gt_f32_e32 vcc, s23, v16
	s_nop 1
	v_cndmask_b32_e64 v18, 0, 32, vcc
	v_ldexp_f32 v16, v16, v18
	v_log_f32_e32 v16, v16
	s_nop 0
	v_mul_f32_e32 v18, 0x3f317217, v16
	v_fma_f32 v18, v16, s3, -v18
	v_fmac_f32_e32 v18, 0x3377d1cf, v16
	v_fmac_f32_e32 v18, 0x3f317217, v16
	v_cmp_lt_f32_e64 s[0:1], |v16|, s4
	s_nop 1
	v_cndmask_b32_e64 v16, v16, v18, s[0:1]
	v_cndmask_b32_e32 v18, 0, v176, vcc
	v_sub_f32_e32 v16, v16, v18
	v_sub_f32_e32 v18, v17, v16
	s_waitcnt lgkmcnt(11)
	v_fma_f32 v19, v67, v224, v69
	ds_read2_b32 v[248:249], v70 offset0:136 offset1:137
	v_fmac_f32_e32 v19, v68, v225
	s_waitcnt lgkmcnt(11)
	v_fmac_f32_e32 v19, v63, v226
	ds_read2_b32 v[250:251], v70 offset0:138 offset1:139
	v_fmac_f32_e32 v19, v64, v227
	s_waitcnt lgkmcnt(11)
	v_fmac_f32_e32 v19, v65, v228
	ds_read2_b32 v[74:75], v70 offset0:140 offset1:141
	v_fmac_f32_e32 v19, v66, v229
	s_waitcnt lgkmcnt(11)
	v_fmac_f32_e32 v19, v61, v230
	ds_read2_b32 v[76:77], v70 offset0:142 offset1:143
	v_fmac_f32_e32 v19, v62, v231
	s_waitcnt lgkmcnt(11)
	v_pk_mul_f32 v[16:17], v[8:9], v[232:233]
	ds_read2_b32 v[78:79], v70 offset0:144 offset1:145
	s_nop 0
	v_add_f32_e32 v16, v19, v16
	v_add_f32_e32 v19, v16, v17
	s_waitcnt lgkmcnt(11)
	v_pk_mul_f32 v[16:17], v[6:7], v[234:235]
	ds_read2_b32 v[80:81], v70 offset0:146 offset1:147
	s_nop 0
	v_add_f32_e32 v16, v19, v16
	v_add_f32_e32 v19, v16, v17
	s_waitcnt lgkmcnt(11)
	v_pk_mul_f32 v[16:17], v[4:5], v[236:237]
	ds_read2_b32 v[82:83], v70 offset0:148 offset1:149
	s_nop 0
	v_add_f32_e32 v16, v19, v16
	v_add_f32_e32 v19, v16, v17
	s_waitcnt lgkmcnt(11)
	v_pk_mul_f32 v[16:17], v[2:3], v[238:239]
	ds_read2_b32 v[84:85], v70 offset0:150 offset1:151
	s_nop 0
	v_add_f32_e32 v16, v19, v16
	v_add_f32_e32 v16, v16, v17
	v_min_f32_e32 v17, 0, v16
	v_mul_f32_e64 v16, |v16|, s2
	v_exp_f32_e32 v16, v16
	s_nop 0
	v_add_f32_e32 v16, 1.0, v16
	v_cmp_gt_f32_e32 vcc, s23, v16
	s_nop 1
	v_cndmask_b32_e64 v19, 0, 32, vcc
	v_ldexp_f32 v16, v16, v19
	v_log_f32_e32 v16, v16
	s_nop 0
	v_mul_f32_e32 v19, 0x3f317217, v16
	v_fma_f32 v19, v16, s3, -v19
	v_fmac_f32_e32 v19, 0x3377d1cf, v16
	v_fmac_f32_e32 v19, 0x3f317217, v16
	v_cmp_lt_f32_e64 s[0:1], |v16|, s4
	s_nop 1
	v_cndmask_b32_e64 v16, v16, v19, s[0:1]
	v_cndmask_b32_e32 v19, 0, v176, vcc
	v_sub_f32_e32 v16, v16, v19
	v_sub_f32_e32 v17, v17, v16
	v_fmamk_f32 v16, v18, 0x3d800000, v15
	v_fmamk_f32 v17, v17, 0x3d800000, v16
	s_waitcnt lgkmcnt(11)
	v_fma_f32 v20, v67, v240, v69
	ds_read2_b32 v[86:87], v70 offset0:152 offset1:153
	v_fmac_f32_e32 v20, v68, v241
	s_waitcnt lgkmcnt(11)
	v_fmac_f32_e32 v20, v63, v242
	ds_read2_b32 v[88:89], v70 offset0:154 offset1:155
	v_fmac_f32_e32 v20, v64, v243
	s_waitcnt lgkmcnt(11)
	v_fmac_f32_e32 v20, v65, v244
	ds_read2_b32 v[90:91], v70 offset0:156 offset1:157
	v_fmac_f32_e32 v20, v66, v245
	s_waitcnt lgkmcnt(11)
	v_fmac_f32_e32 v20, v61, v246
	ds_read2_b32 v[92:93], v70 offset0:158 offset1:159
	v_fmac_f32_e32 v20, v62, v247
	s_waitcnt lgkmcnt(11)
	v_pk_mul_f32 v[18:19], v[8:9], v[248:249]
	ds_read2_b32 v[94:95], v70 offset0:160 offset1:161
	s_nop 0
	v_add_f32_e32 v18, v20, v18
	v_add_f32_e32 v20, v18, v19
	s_waitcnt lgkmcnt(11)
	v_pk_mul_f32 v[18:19], v[6:7], v[250:251]
	ds_read2_b32 v[96:97], v70 offset0:162 offset1:163
	s_nop 0
	v_add_f32_e32 v18, v20, v18
	v_add_f32_e32 v20, v18, v19
	s_waitcnt lgkmcnt(11)
	v_pk_mul_f32 v[18:19], v[4:5], v[74:75]
	ds_read2_b32 v[98:99], v70 offset0:164 offset1:165
	s_nop 0
	v_add_f32_e32 v18, v20, v18
	v_add_f32_e32 v20, v18, v19
	s_waitcnt lgkmcnt(11)
	v_pk_mul_f32 v[18:19], v[2:3], v[76:77]
	ds_read2_b32 v[100:101], v70 offset0:166 offset1:167
	s_nop 0
	v_add_f32_e32 v18, v20, v18
	v_add_f32_e32 v18, v18, v19
	v_min_f32_e32 v19, 0, v18
	v_mul_f32_e64 v18, |v18|, s2
	v_exp_f32_e32 v18, v18
	s_nop 0
	v_add_f32_e32 v18, 1.0, v18
	v_cmp_gt_f32_e32 vcc, s23, v18
	s_nop 1
	v_cndmask_b32_e64 v20, 0, 32, vcc
	v_ldexp_f32 v18, v18, v20
	v_log_f32_e32 v18, v18
	s_nop 0
	v_mul_f32_e32 v20, 0x3f317217, v18
	v_fma_f32 v20, v18, s3, -v20
	v_fmac_f32_e32 v20, 0x3377d1cf, v18
	v_fmac_f32_e32 v20, 0x3f317217, v18
	v_cmp_lt_f32_e64 s[0:1], |v18|, s4
	s_nop 1
	v_cndmask_b32_e64 v18, v18, v20, s[0:1]
	v_cndmask_b32_e32 v20, 0, v176, vcc
	v_sub_f32_e32 v18, v18, v20
	v_sub_f32_e32 v20, v19, v18
	s_waitcnt lgkmcnt(11)
; DI void gla_prep_item(const P& p, int l, int item, unsigned char* smem) {
;     ...
;     for (int ii = 0; ii < 16; ++ii) {
;         const int i = 16 * half + ii; float z = bdv;
; #pragma unroll
;         for (int r = 0; r < 16; ++r) z += slr[i * 16 + r] * wd[r];
;         const float ls = fminf(z, 0.f) - __logf(1.f + __expf(-fabsf(z)));
;         run += ls * (1.f / 16.f); cum[ii] = run;
;     }
	v_fma_f32 v21, v67, v78, v69
	ds_read2_b32 v[102:103], v70 offset0:168 offset1:169
	v_fmac_f32_e32 v21, v68, v79
	s_waitcnt lgkmcnt(11)
	v_fmac_f32_e32 v21, v63, v80
	ds_read2_b32 v[104:105], v70 offset0:170 offset1:171
	v_fmac_f32_e32 v21, v64, v81
	s_waitcnt lgkmcnt(11)
	v_fmac_f32_e32 v21, v65, v82
	ds_read2_b32 v[106:107], v70 offset0:172 offset1:173
	v_fmac_f32_e32 v21, v66, v83
	s_waitcnt lgkmcnt(11)
	v_fmac_f32_e32 v21, v61, v84
	ds_read2_b32 v[108:109], v70 offset0:174 offset1:175
	v_fmac_f32_e32 v21, v62, v85
	s_waitcnt lgkmcnt(11)
	v_pk_mul_f32 v[18:19], v[8:9], v[86:87]
	ds_read2_b32 v[112:113], v70 offset0:176 offset1:177
	s_nop 0
	v_add_f32_e32 v18, v21, v18
	v_add_f32_e32 v21, v18, v19
	s_waitcnt lgkmcnt(11)
	v_pk_mul_f32 v[18:19], v[6:7], v[88:89]
	ds_read2_b32 v[114:115], v70 offset0:178 offset1:179
	s_nop 0
	v_add_f32_e32 v18, v21, v18
	v_add_f32_e32 v21, v18, v19
	s_waitcnt lgkmcnt(11)
	v_pk_mul_f32 v[18:19], v[4:5], v[90:91]
	ds_read2_b32 v[116:117], v70 offset0:180 offset1:181
	s_nop 0
	v_add_f32_e32 v18, v21, v18
	v_add_f32_e32 v21, v18, v19
	s_waitcnt lgkmcnt(11)
	v_pk_mul_f32 v[18:19], v[2:3], v[92:93]
	ds_read2_b32 v[118:119], v70 offset0:182 offset1:183
	s_nop 0
	v_add_f32_e32 v18, v21, v18
	v_add_f32_e32 v18, v18, v19
	v_min_f32_e32 v19, 0, v18
	v_mul_f32_e64 v18, |v18|, s2
	v_exp_f32_e32 v18, v18
	s_nop 0
	v_add_f32_e32 v18, 1.0, v18
	v_cmp_gt_f32_e32 vcc, s23, v18
	s_nop 1
	v_cndmask_b32_e64 v21, 0, 32, vcc
	v_ldexp_f32 v18, v18, v21
	v_log_f32_e32 v18, v18
	s_nop 0
	v_mul_f32_e32 v21, 0x3f317217, v18
	v_fma_f32 v21, v18, s3, -v21
	v_fmac_f32_e32 v21, 0x3377d1cf, v18
	v_fmac_f32_e32 v21, 0x3f317217, v18
	v_cmp_lt_f32_e64 s[0:1], |v18|, s4
	s_nop 1
	v_cndmask_b32_e64 v18, v18, v21, s[0:1]
	v_cndmask_b32_e32 v21, 0, v176, vcc
	v_sub_f32_e32 v18, v18, v21
	v_sub_f32_e32 v19, v19, v18
	v_fmamk_f32 v18, v20, 0x3d800000, v17
	v_fmamk_f32 v19, v19, 0x3d800000, v18
	s_waitcnt lgkmcnt(11)
	v_fma_f32 v22, v67, v94, v69
	ds_read2_b32 v[120:121], v70 offset0:184 offset1:185
	v_fmac_f32_e32 v22, v68, v95
	s_waitcnt lgkmcnt(11)
	v_fmac_f32_e32 v22, v63, v96
	ds_read2_b32 v[122:123], v70 offset0:186 offset1:187
	v_fmac_f32_e32 v22, v64, v97
	s_waitcnt lgkmcnt(11)
	v_fmac_f32_e32 v22, v65, v98
	ds_read2_b32 v[124:125], v70 offset0:188 offset1:189
	v_fmac_f32_e32 v22, v66, v99
	s_waitcnt lgkmcnt(11)
	v_fmac_f32_e32 v22, v61, v100
	ds_read2_b32 v[126:127], v70 offset0:190 offset1:191
	v_fmac_f32_e32 v22, v62, v101
	s_waitcnt lgkmcnt(11)
	v_pk_mul_f32 v[20:21], v[8:9], v[102:103]
	ds_read2_b32 v[142:143], v70 offset0:192 offset1:193
	s_nop 0
	v_add_f32_e32 v20, v22, v20
	v_add_f32_e32 v22, v20, v21
	s_waitcnt lgkmcnt(11)
	v_pk_mul_f32 v[20:21], v[6:7], v[104:105]
	ds_read2_b32 v[144:145], v70 offset0:194 offset1:195
	s_nop 0
	v_add_f32_e32 v20, v22, v20
	v_add_f32_e32 v22, v20, v21
	s_waitcnt lgkmcnt(11)
	v_pk_mul_f32 v[20:21], v[4:5], v[106:107]
	ds_read2_b32 v[146:147], v70 offset0:196 offset1:197
	s_nop 0
	v_add_f32_e32 v20, v22, v20
	v_add_f32_e32 v22, v20, v21
	s_waitcnt lgkmcnt(11)
	v_pk_mul_f32 v[20:21], v[2:3], v[108:109]
	ds_read2_b32 v[148:149], v70 offset0:198 offset1:199
	s_nop 0
	v_add_f32_e32 v20, v22, v20
	v_add_f32_e32 v20, v20, v21
	v_min_f32_e32 v21, 0, v20
	v_mul_f32_e64 v20, |v20|, s2
	v_exp_f32_e32 v20, v20
	s_nop 0
	v_add_f32_e32 v20, 1.0, v20
	v_cmp_gt_f32_e32 vcc, s23, v20
	s_nop 1
	v_cndmask_b32_e64 v22, 0, 32, vcc
	v_ldexp_f32 v20, v20, v22
	v_log_f32_e32 v20, v20
	s_nop 0
	v_mul_f32_e32 v22, 0x3f317217, v20
	v_fma_f32 v22, v20, s3, -v22
	v_fmac_f32_e32 v22, 0x3377d1cf, v20
	v_fmac_f32_e32 v22, 0x3f317217, v20
	v_cmp_lt_f32_e64 s[0:1], |v20|, s4
	s_nop 1
	v_cndmask_b32_e64 v20, v20, v22, s[0:1]
	v_cndmask_b32_e32 v22, 0, v176, vcc
	v_sub_f32_e32 v20, v20, v22
	v_sub_f32_e32 v22, v21, v20
	s_waitcnt lgkmcnt(11)
	v_fma_f32 v23, v67, v112, v69
	ds_read2_b32 v[150:151], v70 offset0:200 offset1:201
	v_fmac_f32_e32 v23, v68, v113
	s_waitcnt lgkmcnt(11)
	v_fmac_f32_e32 v23, v63, v114
	ds_read2_b32 v[152:153], v70 offset0:202 offset1:203
	v_fmac_f32_e32 v23, v64, v115
	s_waitcnt lgkmcnt(11)
	v_fmac_f32_e32 v23, v65, v116
	ds_read2_b32 v[154:155], v70 offset0:204 offset1:205
	v_fmac_f32_e32 v23, v66, v117
	s_waitcnt lgkmcnt(11)
	v_fmac_f32_e32 v23, v61, v118
	ds_read2_b32 v[156:157], v70 offset0:206 offset1:207
	v_fmac_f32_e32 v23, v62, v119
	s_waitcnt lgkmcnt(11)
	v_pk_mul_f32 v[20:21], v[8:9], v[120:121]
	ds_read2_b32 v[158:159], v70 offset0:208 offset1:209
	s_nop 0
	v_add_f32_e32 v20, v23, v20
	v_add_f32_e32 v23, v20, v21
	s_waitcnt lgkmcnt(11)
	v_pk_mul_f32 v[20:21], v[6:7], v[122:123]
	ds_read2_b32 v[160:161], v70 offset0:210 offset1:211
	s_nop 0
	v_add_f32_e32 v20, v23, v20
	v_add_f32_e32 v23, v20, v21
	s_waitcnt lgkmcnt(11)
	v_pk_mul_f32 v[20:21], v[4:5], v[124:125]
	ds_read2_b32 v[162:163], v70 offset0:212 offset1:213
	s_nop 0
	v_add_f32_e32 v20, v23, v20
	v_add_f32_e32 v23, v20, v21
	s_waitcnt lgkmcnt(11)
	v_pk_mul_f32 v[20:21], v[2:3], v[126:127]
	ds_read2_b32 v[164:165], v70 offset0:214 offset1:215
	s_nop 0
	v_add_f32_e32 v20, v23, v20
	v_add_f32_e32 v20, v20, v21
	v_min_f32_e32 v21, 0, v20
	v_mul_f32_e64 v20, |v20|, s2
	v_exp_f32_e32 v20, v20
	s_nop 0
	v_add_f32_e32 v20, 1.0, v20
	v_cmp_gt_f32_e32 vcc, s23, v20
	s_nop 1
	v_cndmask_b32_e64 v23, 0, 32, vcc
	v_ldexp_f32 v20, v20, v23
	v_log_f32_e32 v20, v20
	s_nop 0
	v_mul_f32_e32 v23, 0x3f317217, v20
	v_fma_f32 v23, v20, s3, -v23
	v_fmac_f32_e32 v23, 0x3377d1cf, v20
	v_fmac_f32_e32 v23, 0x3f317217, v20
	v_cmp_lt_f32_e64 s[0:1], |v20|, s4
	s_nop 1
	v_cndmask_b32_e64 v20, v20, v23, s[0:1]
	v_cndmask_b32_e32 v23, 0, v176, vcc
	v_sub_f32_e32 v20, v20, v23
	v_sub_f32_e32 v21, v21, v20
	v_fmamk_f32 v20, v22, 0x3d800000, v19
	v_fmamk_f32 v21, v21, 0x3d800000, v20
	s_waitcnt lgkmcnt(11)
; DI void gla_prep_item(const P& p, int l, int item, unsigned char* smem) {
;     ...
;     for (int ii = 0; ii < 16; ++ii) {
;         const int i = 16 * half + ii; float z = bdv;
; #pragma unroll
;         for (int r = 0; r < 16; ++r) z += slr[i * 16 + r] * wd[r];
;         const float ls = fminf(z, 0.f) - __logf(1.f + __expf(-fabsf(z)));
;         run += ls * (1.f / 16.f); cum[ii] = run;
;     }
	v_fma_f32 v71, v67, v142, v69
	ds_read2_b32 v[184:185], v70 offset0:216 offset1:217
	v_fmac_f32_e32 v71, v68, v143
	s_waitcnt lgkmcnt(11)
	v_fmac_f32_e32 v71, v63, v144
	ds_read2_b32 v[186:187], v70 offset0:218 offset1:219
	v_fmac_f32_e32 v71, v64, v145
	s_waitcnt lgkmcnt(11)
	v_fmac_f32_e32 v71, v65, v146
	ds_read2_b32 v[188:189], v70 offset0:220 offset1:221
	v_fmac_f32_e32 v71, v66, v147
	s_waitcnt lgkmcnt(11)
	v_fmac_f32_e32 v71, v61, v148
	ds_read2_b32 v[190:191], v70 offset0:222 offset1:223
	v_fmac_f32_e32 v71, v62, v149
	s_waitcnt lgkmcnt(11)
	v_pk_mul_f32 v[22:23], v[8:9], v[150:151]
	ds_read2_b32 v[192:193], v70 offset0:224 offset1:225
	s_nop 0
	v_add_f32_e32 v22, v71, v22
	v_add_f32_e32 v71, v22, v23
	s_waitcnt lgkmcnt(11)
	v_pk_mul_f32 v[22:23], v[6:7], v[152:153]
	ds_read2_b32 v[194:195], v70 offset0:226 offset1:227
	s_nop 0
	v_add_f32_e32 v22, v71, v22
	v_add_f32_e32 v71, v22, v23
	s_waitcnt lgkmcnt(11)
	v_pk_mul_f32 v[22:23], v[4:5], v[154:155]
	ds_read2_b32 v[196:197], v70 offset0:228 offset1:229
	s_nop 0
	v_add_f32_e32 v22, v71, v22
	v_add_f32_e32 v71, v22, v23
	s_waitcnt lgkmcnt(11)
	v_pk_mul_f32 v[22:23], v[2:3], v[156:157]
	ds_read2_b32 v[198:199], v70 offset0:230 offset1:231
	s_nop 0
	v_add_f32_e32 v22, v71, v22
	v_add_f32_e32 v22, v22, v23
	v_min_f32_e32 v23, 0, v22
	v_mul_f32_e64 v22, |v22|, s2
	v_exp_f32_e32 v22, v22
	s_nop 0
	v_add_f32_e32 v22, 1.0, v22
	v_cmp_gt_f32_e32 vcc, s23, v22
	s_nop 1
	v_cndmask_b32_e64 v71, 0, 32, vcc
	v_ldexp_f32 v22, v22, v71
	v_log_f32_e32 v22, v22
	s_nop 0
	v_mul_f32_e32 v71, 0x3f317217, v22
	v_fma_f32 v71, v22, s3, -v71
	v_fmac_f32_e32 v71, 0x3377d1cf, v22
	v_fmac_f32_e32 v71, 0x3f317217, v22
	v_cmp_lt_f32_e64 s[0:1], |v22|, s4
	s_nop 1
	v_cndmask_b32_e64 v22, v22, v71, s[0:1]
	v_cndmask_b32_e32 v71, 0, v176, vcc
	v_sub_f32_e32 v22, v22, v71
	v_sub_f32_e32 v71, v23, v22
	s_waitcnt lgkmcnt(11)
	v_fma_f32 v72, v67, v158, v69
	ds_read2_b32 v[200:201], v70 offset0:232 offset1:233
	v_fmac_f32_e32 v72, v68, v159
	s_waitcnt lgkmcnt(11)
	v_fmac_f32_e32 v72, v63, v160
	ds_read2_b32 v[202:203], v70 offset0:234 offset1:235
	v_fmac_f32_e32 v72, v64, v161
	s_waitcnt lgkmcnt(11)
	v_fmac_f32_e32 v72, v65, v162
	ds_read2_b32 v[204:205], v70 offset0:236 offset1:237
	v_fmac_f32_e32 v72, v66, v163
	s_waitcnt lgkmcnt(11)
	v_fmac_f32_e32 v72, v61, v164
	ds_read2_b32 v[206:207], v70 offset0:238 offset1:239
	v_fmac_f32_e32 v72, v62, v165
	s_waitcnt lgkmcnt(11)
	v_pk_mul_f32 v[22:23], v[8:9], v[184:185]
	ds_read2_b32 v[208:209], v70 offset0:240 offset1:241
	s_nop 0
	v_add_f32_e32 v22, v72, v22
	v_add_f32_e32 v72, v22, v23
	s_waitcnt lgkmcnt(11)
	v_pk_mul_f32 v[22:23], v[6:7], v[186:187]
	ds_read2_b32 v[210:211], v70 offset0:242 offset1:243
	s_nop 0
	v_add_f32_e32 v22, v72, v22
	v_add_f32_e32 v72, v22, v23
	s_waitcnt lgkmcnt(11)
	v_pk_mul_f32 v[22:23], v[4:5], v[188:189]
	ds_read2_b32 v[212:213], v70 offset0:248 offset1:249
	s_nop 0
	v_add_f32_e32 v22, v72, v22
	v_add_f32_e32 v72, v22, v23
	s_waitcnt lgkmcnt(11)
	v_pk_mul_f32 v[22:23], v[2:3], v[190:191]
	ds_read2_b32 v[214:215], v70 offset0:250 offset1:251
	s_nop 0
	v_add_f32_e32 v22, v72, v22
	v_add_f32_e32 v22, v22, v23
	v_min_f32_e32 v23, 0, v22
	v_mul_f32_e64 v22, |v22|, s2
	v_exp_f32_e32 v22, v22
	s_nop 0
	v_add_f32_e32 v22, 1.0, v22
	v_cmp_gt_f32_e32 vcc, s23, v22
	s_nop 1
	v_cndmask_b32_e64 v72, 0, 32, vcc
	v_ldexp_f32 v22, v22, v72
	v_log_f32_e32 v22, v22
	s_nop 0
	v_mul_f32_e32 v72, 0x3f317217, v22
	v_fma_f32 v72, v22, s3, -v72
	v_fmac_f32_e32 v72, 0x3377d1cf, v22
	v_fmac_f32_e32 v72, 0x3f317217, v22
	v_cmp_lt_f32_e64 s[0:1], |v22|, s4
	s_nop 1
	v_cndmask_b32_e64 v22, v22, v72, s[0:1]
	v_cndmask_b32_e32 v72, 0, v176, vcc
	v_sub_f32_e32 v22, v22, v72
	v_sub_f32_e32 v23, v23, v22
	v_fmamk_f32 v22, v71, 0x3d800000, v21
	v_fmamk_f32 v23, v23, 0x3d800000, v22
	s_waitcnt lgkmcnt(11)
	v_fma_f32 v71, v67, v192, v69
	ds_read2_b32 v[216:217], v70 offset0:252 offset1:253
	v_fmac_f32_e32 v71, v68, v193
	s_waitcnt lgkmcnt(11)
	v_fmac_f32_e32 v71, v63, v194
	ds_read_b32 v218, v70 offset:1016
	v_fmac_f32_e32 v71, v64, v195
	s_waitcnt lgkmcnt(11)
	v_fmac_f32_e32 v71, v65, v196
	v_fmac_f32_e32 v71, v66, v197
	s_waitcnt lgkmcnt(10)
	v_fmac_f32_e32 v71, v61, v198
	v_fmac_f32_e32 v71, v62, v199
	s_waitcnt lgkmcnt(9)
	v_pk_mul_f32 v[72:73], v[8:9], v[200:201]
	s_nop 0
	v_add_f32_e32 v71, v71, v72
	v_add_f32_e32 v71, v71, v73
	s_waitcnt lgkmcnt(8)
	v_pk_mul_f32 v[72:73], v[6:7], v[202:203]
	s_nop 0
	v_add_f32_e32 v71, v71, v72
	v_add_f32_e32 v71, v71, v73
	s_waitcnt lgkmcnt(7)
	v_pk_mul_f32 v[72:73], v[4:5], v[204:205]
	s_nop 0
	v_add_f32_e32 v71, v71, v72
	v_add_f32_e32 v71, v71, v73
	s_waitcnt lgkmcnt(6)
	v_pk_mul_f32 v[72:73], v[2:3], v[206:207]
	s_nop 0
	v_add_f32_e32 v71, v71, v72
	v_add_f32_e32 v71, v71, v73
	v_min_f32_e32 v72, 0, v71
	v_mul_f32_e64 v71, |v71|, s2
	v_exp_f32_e32 v71, v71
	s_nop 0
	v_add_f32_e32 v71, 1.0, v71
	v_cmp_gt_f32_e32 vcc, s23, v71
	s_nop 1
	v_cndmask_b32_e64 v73, 0, 32, vcc
	v_ldexp_f32 v71, v71, v73
	v_log_f32_e32 v71, v71
	s_nop 0
	v_mul_f32_e32 v73, 0x3f317217, v71
	v_fma_f32 v73, v71, s3, -v73
	v_fmac_f32_e32 v73, 0x3377d1cf, v71
	v_fmac_f32_e32 v73, 0x3f317217, v71
	v_cmp_lt_f32_e64 s[0:1], |v71|, s4
	s_nop 1
	v_cndmask_b32_e64 v71, v71, v73, s[0:1]
	v_cndmask_b32_e32 v73, 0, v176, vcc
	v_sub_f32_e32 v71, v71, v73
	v_sub_f32_e32 v71, v72, v71
	ds_read2_b32 v[72:73], v70 offset0:244 offset1:245
	s_waitcnt lgkmcnt(6)
	v_fmac_f32_e32 v69, v67, v208
	v_fmac_f32_e32 v69, v68, v209
	s_waitcnt lgkmcnt(5)
	v_fmac_f32_e32 v69, v63, v210
	v_fmac_f32_e32 v69, v64, v211
	s_waitcnt lgkmcnt(0)
; DI float bf2f(bf16_t b) { return __uint_as_float(((unsigned)b) << 16); }
; DI void gla_prep_item(const P& p, int l, int item, unsigned char* smem) {
;     ...
;         const float ls = fminf(z, 0.f) - __logf(1.f + __expf(-fabsf(z)));
;         run += ls * (1.f / 16.f); cum[ii] = run;
;     }
;     if (half == 0) stot[cch] = run;
;     __syncthreads();
;     if (half == 1) { const float t = stot[cch];
; #pragma unroll
;         for (int ii = 0; ii < 16; ++ii) cum[ii] += t;
;         slast[cch] = cum[15]; }
;     __syncthreads();
;     const float cl = slast[cch];
;     const int seq = (dir * 4 + b) * 4 + h;
; #pragma unroll
;     for (int ii = 0; ii < 16; ++ii) {
;         const int i = 16 * half + ii, pp = 32 * c + i;
;         const float q = bf2f(qraw[ii]) * 0.125f, k = bf2f(kraw[ii]);
;         const float qt = q * __expf(cum[ii]), kt = k * __expf(-cum[ii]), ko = k * __expf(cl - cum[ii]);
;         QT[((size_t)seq * PT + pp) * 64 + d] = f2bf(qt); KO[((size_t)seq * PT + pp) * 64 + d] = f2bf(ko);
;         sq[(h * 32 + i) * 72 + d] = f2bf(qt); sk[(h * 32 + i) * 72 + d] = f2bf(kt);
	v_fmac_f32_e32 v69, v65, v72
	ds_read2_b32 v[64:65], v70 offset0:246 offset1:247
	v_fmac_f32_e32 v69, v66, v73
	s_waitcnt lgkmcnt(0)
	v_fmac_f32_e32 v69, v61, v64
	v_fmac_f32_e32 v69, v62, v65
	v_pk_mul_f32 v[8:9], v[8:9], v[212:213]
	s_nop 0
	v_add_f32_e32 v8, v69, v8
	v_add_f32_e32 v61, v8, v9
	v_pk_mul_f32 v[6:7], v[6:7], v[214:215]
	s_nop 0
	v_add_f32_e32 v6, v61, v6
	v_add_f32_e32 v8, v6, v7
	v_pk_mul_f32 v[4:5], v[4:5], v[216:217]
	s_nop 0
	v_add_f32_e32 v4, v8, v4
	v_add_f32_e32 v6, v4, v5
	v_or_b32_e32 v5, 0x3fc, v43
	v_add_u32_e32 v5, s26, v5
	ds_read_b32 v219, v5
	s_waitcnt lgkmcnt(0)
	v_pk_mul_f32 v[2:3], v[2:3], v[218:219]
	s_nop 0
	v_add_f32_e32 v2, v6, v2
	v_add_f32_e32 v2, v2, v3
	v_min_f32_e32 v3, 0, v2
	v_mul_f32_e64 v2, |v2|, s2
	v_exp_f32_e32 v2, v2
	v_lshl_add_u32 v5, v1, 2, s26
	v_add_f32_e32 v2, 1.0, v2
	v_cmp_gt_f32_e32 vcc, s23, v2
	s_nop 1
	v_cndmask_b32_e64 v4, 0, 32, vcc
	v_ldexp_f32 v2, v2, v4
	v_log_f32_e32 v2, v2
	s_nop 0
	v_mul_f32_e32 v4, 0x3f317217, v2
	v_fma_f32 v4, v2, s3, -v4
	v_fmac_f32_e32 v4, 0x3377d1cf, v2
	v_fmac_f32_e32 v4, 0x3f317217, v2
	v_cmp_lt_f32_e64 s[0:1], |v2|, s4
	s_nop 1
	v_cndmask_b32_e64 v2, v2, v4, s[0:1]
	v_cndmask_b32_e32 v4, 0, v176, vcc
	v_sub_f32_e32 v2, v2, v4
	v_sub_f32_e32 v3, v3, v2
	v_fmamk_f32 v2, v71, 0x3d800000, v23
	v_fmamk_f32 v3, v3, 0x3d800000, v2
	v_cmp_gt_u32_e32 vcc, s5, v24
	s_and_saveexec_b64 s[0:1], vcc
	ds_write_b32 v5, v3 offset:2048
	s_or_b64 exec, exec, s[0:1]
	s_lshl_b32 s2, s24, 4
	v_cmp_eq_u32_e64 s[0:1], 1, v37
	s_waitcnt lgkmcnt(0)
	s_waitcnt lgkmcnt(0)
	s_barrier
	s_and_saveexec_b64 s[36:37], s[0:1]
	s_cbranch_execz .LBB0_262
	ds_read_b32 v4, v5 offset:2048
	s_waitcnt lgkmcnt(0)
	v_pk_add_f32 v[10:11], v[10:11], v[4:5] op_sel_hi:[1,0]
	v_pk_add_f32 v[12:13], v[12:13], v[4:5] op_sel_hi:[1,0]
	v_pk_add_f32 v[14:15], v[14:15], v[4:5] op_sel_hi:[1,0]
	v_pk_add_f32 v[16:17], v[16:17], v[4:5] op_sel_hi:[1,0]
	v_pk_add_f32 v[18:19], v[18:19], v[4:5] op_sel_hi:[1,0]
	v_pk_add_f32 v[20:21], v[20:21], v[4:5] op_sel_hi:[1,0]
	v_pk_add_f32 v[22:23], v[22:23], v[4:5] op_sel_hi:[1,0]
	v_pk_add_f32 v[2:3], v[2:3], v[4:5] op_sel_hi:[1,0]
	ds_write_b32 v5, v3 offset:3072
.LBB0_262:
	s_or_b64 exec, exec, s[36:37]
	s_waitcnt lgkmcnt(0)
	s_barrier
	ds_read_b32 v6, v5 offset:3072
	s_add_u32 s0, s42, 0x1163c000
	s_addc_u32 s1, s43, 0
	s_add_u32 s36, s42, 0x11f3c000
	v_mul_f32_e32 v8, 0x3fb8aa3b, v10
	v_mul_f32_e32 v9, 0xbfb8aa3b, v10
	s_waitcnt lgkmcnt(0)
	v_sub_f32_e32 v10, v6, v10
	s_addc_u32 s37, s43, 0
	s_lshl_b32 s3, s22, 2
	v_exp_f32_e32 v8, v8
	v_mul_f32_e32 v10, 0x3fb8aa3b, v10
	v_lshrrev_b32_e32 v1, 6, v1
	s_add_i32 s2, s2, s3
	v_exp_f32_e32 v9, v9
	v_exp_f32_e32 v10, v10
	v_or_b32_e32 v5, s2, v1
	v_lshlrev_b32_e32 v7, 5, v1
	v_lshlrev_b32_e32 v1, 16, v29
	v_mul_f32_e32 v1, 0x3e000000, v1
	v_lshlrev_b32_e32 v27, 16, v27
	v_mul_f32_e32 v1, v1, v8
	v_mul_u32_u24_e32 v132, 0x900, v5
	v_mul_f32_e32 v29, v9, v27
	v_mul_f32_e32 v10, v10, v27
	v_cvt_pk_bf16_f32 v27, v1, s0
	v_ashrrev_i32_e32 v1, 31, v0
	v_and_b32_e32 v4, 63, v24
	v_lshl_add_u64 v[0:1], v[132:133], 0, v[0:1]
	v_lshlrev_b64 v[8:9], 7, v[0:1]
	v_lshlrev_b32_e32 v0, 1, v4
	v_or_b32_e32 v8, v8, v0
	v_lshl_add_u64 v[62:63], s[0:1], 0, v[8:9]
	v_cvt_pk_bf16_f32 v1, v10, s0
	v_lshl_add_u64 v[8:9], s[36:37], 0, v[8:9]
	global_store_short v[8:9], v1, off
	v_add_u32_e32 v1, v7, v26
	s_movk_i32 s3, 0x48
	v_mul_f32_e32 v10, 0x3fb8aa3b, v11
	v_mul_lo_u32 v1, v1, s3
	v_exp_f32_e32 v10, v10
	v_or_b32_e32 v1, v1, v4
	v_lshl_add_u32 v1, v1, 1, s26
	v_cvt_pk_bf16_f32 v8, v29, s0
	v_lshlrev_b32_e32 v9, 16, v30
	global_store_short v[62:63], v27, off
	ds_write_b16 v1, v27 offset:4096
	ds_write_b16 v1, v8 offset:22528
	v_or_b32_e32 v1, 1, v26
	v_mul_f32_e32 v9, 0x3e000000, v9
	v_mul_f32_e32 v27, 0xbfb8aa3b, v11
	v_sub_f32_e32 v11, v6, v11
	v_add_u32_e32 v8, s38, v1
	v_mul_f32_e32 v11, 0x3fb8aa3b, v11
	v_mul_f32_e32 v9, v9, v10
	v_exp_f32_e32 v27, v27
	v_exp_f32_e32 v11, v11
	v_cvt_pk_bf16_f32 v29, v9, s0
	v_ashrrev_i32_e32 v9, 31, v8
	v_lshl_add_u64 v[8:9], v[8:9], 0, v[132:133]
	v_lshlrev_b64 v[8:9], 7, v[8:9]
	v_lshlrev_b32_e32 v28, 16, v28
	v_or_b32_e32 v8, v8, v0
	v_mul_f32_e32 v27, v27, v28
	v_mul_f32_e32 v28, v11, v28
	v_lshl_add_u64 v[10:11], s[0:1], 0, v[8:9]
	global_store_short v[10:11], v29, off
	v_cvt_pk_bf16_f32 v10, v28, s0
	v_lshl_add_u64 v[8:9], s[36:37], 0, v[8:9]
	global_store_short v[8:9], v10, off
	v_mul_f32_e32 v10, 0x3fb8aa3b, v12
	v_mul_f32_e32 v11, 0xbfb8aa3b, v12
	v_sub_f32_e32 v12, v6, v12
	v_add_u32_e32 v1, v1, v7
	v_exp_f32_e32 v10, v10
	v_mul_f32_e32 v12, 0x3fb8aa3b, v12
	v_mad_u64_u32 v[8:9], s[4:5], v1, s3, v[4:5]
	v_exp_f32_e32 v11, v11
	v_exp_f32_e32 v12, v12
	v_lshl_add_u32 v1, v8, 1, s26
	v_cvt_pk_bf16_f32 v8, v27, s0
	v_lshlrev_b32_e32 v9, 16, v32
	ds_write_b16 v1, v29 offset:4096
	ds_write_b16 v1, v8 offset:22528
	v_or_b32_e32 v1, 2, v26
	v_mul_f32_e32 v9, 0x3e000000, v9
	v_add_u32_e32 v8, s38, v1
	v_lshlrev_b32_e32 v27, 16, v31
	v_mul_f32_e32 v9, v9, v10
	v_mul_f32_e32 v28, v11, v27
	v_mul_f32_e32 v12, v12, v27
	v_cvt_pk_bf16_f32 v27, v9, s0
	v_ashrrev_i32_e32 v9, 31, v8
	v_lshl_add_u64 v[8:9], v[8:9], 0, v[132:133]
	v_lshlrev_b64 v[8:9], 7, v[8:9]
	v_or_b32_e32 v8, v8, v0
	v_lshl_add_u64 v[10:11], s[0:1], 0, v[8:9]
	global_store_short v[10:11], v27, off
	v_cvt_pk_bf16_f32 v10, v12, s0
	v_lshl_add_u64 v[8:9], s[36:37], 0, v[8:9]
	global_store_short v[8:9], v10, off
	v_mul_f32_e32 v10, 0x3fb8aa3b, v13
	v_sub_f32_e32 v12, v6, v13
	v_add_u32_e32 v1, v1, v7
	v_exp_f32_e32 v10, v10
	v_mul_f32_e32 v11, 0xbfb8aa3b, v13
	v_mul_f32_e32 v12, 0x3fb8aa3b, v12
	v_mad_u64_u32 v[8:9], s[4:5], v1, s3, v[4:5]
; DI float bf2f(bf16_t b) { return __uint_as_float(((unsigned)b) << 16); }
; DI void gla_prep_item(const P& p, int l, int item, unsigned char* smem) {
;     ...
;     for (int ii = 0; ii < 16; ++ii) {
;         const int i = 16 * half + ii, pp = 32 * c + i;
;         const float q = bf2f(qraw[ii]) * 0.125f, k = bf2f(kraw[ii]);
;         const float qt = q * __expf(cum[ii]), kt = k * __expf(-cum[ii]), ko = k * __expf(cl - cum[ii]);
;         QT[((size_t)seq * PT + pp) * 64 + d] = f2bf(qt); KO[((size_t)seq * PT + pp) * 64 + d] = f2bf(ko);
;         sq[(h * 32 + i) * 72 + d] = f2bf(qt); sk[(h * 32 + i) * 72 + d] = f2bf(kt);
	v_exp_f32_e32 v11, v11
	v_exp_f32_e32 v12, v12
	v_lshl_add_u32 v1, v8, 1, s26
	v_cvt_pk_bf16_f32 v8, v28, s0
	v_lshlrev_b32_e32 v9, 16, v34
	ds_write_b16 v1, v27 offset:4096
	ds_write_b16 v1, v8 offset:22528
	v_or_b32_e32 v1, 3, v26
	v_mul_f32_e32 v9, 0x3e000000, v9
	v_add_u32_e32 v8, s38, v1
	v_lshlrev_b32_e32 v13, 16, v33
	v_mul_f32_e32 v9, v9, v10
	v_mul_f32_e32 v27, v11, v13
	v_mul_f32_e32 v12, v12, v13
	v_cvt_pk_bf16_f32 v13, v9, s0
	v_ashrrev_i32_e32 v9, 31, v8
	v_lshl_add_u64 v[8:9], v[8:9], 0, v[132:133]
	v_lshlrev_b64 v[8:9], 7, v[8:9]
	v_or_b32_e32 v8, v8, v0
	v_lshl_add_u64 v[10:11], s[0:1], 0, v[8:9]
	global_store_short v[10:11], v13, off
	v_cvt_pk_bf16_f32 v10, v12, s0
	v_lshl_add_u64 v[8:9], s[36:37], 0, v[8:9]
	global_store_short v[8:9], v10, off
	v_mul_f32_e32 v10, 0x3fb8aa3b, v14
	v_sub_f32_e32 v12, v6, v14
	v_add_u32_e32 v1, v1, v7
	v_exp_f32_e32 v10, v10
	v_mul_f32_e32 v11, 0xbfb8aa3b, v14
	v_mul_f32_e32 v12, 0x3fb8aa3b, v12
	v_mad_u64_u32 v[8:9], s[4:5], v1, s3, v[4:5]
	v_exp_f32_e32 v11, v11
	v_exp_f32_e32 v12, v12
	v_lshl_add_u32 v1, v8, 1, s26
	v_cvt_pk_bf16_f32 v8, v27, s0
	v_lshlrev_b32_e32 v9, 16, v60
	ds_write_b16 v1, v13 offset:4096
	ds_write_b16 v1, v8 offset:22528
	v_or_b32_e32 v1, 4, v26
	v_mul_f32_e32 v9, 0x3e000000, v9
	v_add_u32_e32 v8, s38, v1
	v_lshlrev_b32_e32 v13, 16, v59
	v_mul_f32_e32 v9, v9, v10
	v_mul_f32_e32 v14, v11, v13
	v_mul_f32_e32 v12, v12, v13
	v_cvt_pk_bf16_f32 v13, v9, s0
	v_ashrrev_i32_e32 v9, 31, v8
	v_lshl_add_u64 v[8:9], v[8:9], 0, v[132:133]
	v_lshlrev_b64 v[8:9], 7, v[8:9]
	v_or_b32_e32 v8, v8, v0
	v_lshl_add_u64 v[10:11], s[0:1], 0, v[8:9]
	global_store_short v[10:11], v13, off
	v_cvt_pk_bf16_f32 v10, v12, s0
	v_lshl_add_u64 v[8:9], s[36:37], 0, v[8:9]
	global_store_short v[8:9], v10, off
	v_mul_f32_e32 v10, 0x3fb8aa3b, v15
	v_sub_f32_e32 v12, v6, v15
	v_add_u32_e32 v1, v1, v7
	v_exp_f32_e32 v10, v10
	v_mul_f32_e32 v11, 0xbfb8aa3b, v15
	v_mul_f32_e32 v12, 0x3fb8aa3b, v12
	v_mad_u64_u32 v[8:9], s[4:5], v1, s3, v[4:5]
	v_exp_f32_e32 v11, v11
	v_exp_f32_e32 v12, v12
	v_lshl_add_u32 v1, v8, 1, s26
	v_cvt_pk_bf16_f32 v8, v14, s0
	v_lshlrev_b32_e32 v9, 16, v58
	ds_write_b16 v1, v13 offset:4096
	ds_write_b16 v1, v8 offset:22528
	v_or_b32_e32 v1, 5, v26
	v_mul_f32_e32 v9, 0x3e000000, v9
	v_add_u32_e32 v8, s38, v1
	v_lshlrev_b32_e32 v13, 16, v56
	v_mul_f32_e32 v9, v9, v10
	v_mul_f32_e32 v14, v11, v13
	v_mul_f32_e32 v12, v12, v13
	v_cvt_pk_bf16_f32 v13, v9, s0
	v_ashrrev_i32_e32 v9, 31, v8
	v_lshl_add_u64 v[8:9], v[8:9], 0, v[132:133]
	v_lshlrev_b64 v[8:9], 7, v[8:9]
	v_or_b32_e32 v8, v8, v0
	v_lshl_add_u64 v[10:11], s[0:1], 0, v[8:9]
	global_store_short v[10:11], v13, off
	v_cvt_pk_bf16_f32 v10, v12, s0
	v_lshl_add_u64 v[8:9], s[36:37], 0, v[8:9]
	global_store_short v[8:9], v10, off
	v_mul_f32_e32 v10, 0x3fb8aa3b, v16
	v_sub_f32_e32 v12, v6, v16
	v_add_u32_e32 v1, v1, v7
	v_exp_f32_e32 v10, v10
	v_mul_f32_e32 v11, 0xbfb8aa3b, v16
	v_mul_f32_e32 v12, 0x3fb8aa3b, v12
	v_mad_u64_u32 v[8:9], s[4:5], v1, s3, v[4:5]
	v_exp_f32_e32 v11, v11
	v_exp_f32_e32 v12, v12
	v_lshl_add_u32 v1, v8, 1, s26
	v_cvt_pk_bf16_f32 v8, v14, s0
	v_lshlrev_b32_e32 v9, 16, v55
	ds_write_b16 v1, v13 offset:4096
	ds_write_b16 v1, v8 offset:22528
	v_or_b32_e32 v1, 6, v26
	v_mul_f32_e32 v9, 0x3e000000, v9
	v_add_u32_e32 v8, s38, v1
	v_lshlrev_b32_e32 v13, 16, v53
	v_mul_f32_e32 v9, v9, v10
	v_mul_f32_e32 v14, v11, v13
	v_mul_f32_e32 v12, v12, v13
	v_cvt_pk_bf16_f32 v13, v9, s0
	v_ashrrev_i32_e32 v9, 31, v8
	v_lshl_add_u64 v[8:9], v[8:9], 0, v[132:133]
	v_lshlrev_b64 v[8:9], 7, v[8:9]
	v_or_b32_e32 v8, v8, v0
	v_lshl_add_u64 v[10:11], s[0:1], 0, v[8:9]
	global_store_short v[10:11], v13, off
	v_cvt_pk_bf16_f32 v10, v12, s0
	v_lshl_add_u64 v[8:9], s[36:37], 0, v[8:9]
	global_store_short v[8:9], v10, off
	v_mul_f32_e32 v10, 0x3fb8aa3b, v17
	v_sub_f32_e32 v12, v6, v17
	v_add_u32_e32 v1, v1, v7
	v_exp_f32_e32 v10, v10
	v_mul_f32_e32 v11, 0xbfb8aa3b, v17
	v_mul_f32_e32 v12, 0x3fb8aa3b, v12
	v_mad_u64_u32 v[8:9], s[4:5], v1, s3, v[4:5]
	v_exp_f32_e32 v11, v11
	v_exp_f32_e32 v12, v12
	v_lshl_add_u32 v1, v8, 1, s26
	v_cvt_pk_bf16_f32 v8, v14, s0
	v_lshlrev_b32_e32 v9, 16, v57
	ds_write_b16 v1, v13 offset:4096
	ds_write_b16 v1, v8 offset:22528
	v_or_b32_e32 v1, 7, v26
	v_mul_f32_e32 v9, 0x3e000000, v9
	v_add_u32_e32 v8, s38, v1
	v_lshlrev_b32_e32 v13, 16, v54
	v_mul_f32_e32 v9, v9, v10
	v_mul_f32_e32 v14, v11, v13
	v_mul_f32_e32 v12, v12, v13
	v_cvt_pk_bf16_f32 v13, v9, s0
	v_ashrrev_i32_e32 v9, 31, v8
	v_lshl_add_u64 v[8:9], v[8:9], 0, v[132:133]
	v_lshlrev_b64 v[8:9], 7, v[8:9]
	v_or_b32_e32 v8, v8, v0
	v_lshl_add_u64 v[10:11], s[0:1], 0, v[8:9]
	global_store_short v[10:11], v13, off
	v_cvt_pk_bf16_f32 v10, v12, s0
	v_lshl_add_u64 v[8:9], s[36:37], 0, v[8:9]
	global_store_short v[8:9], v10, off
	v_mul_f32_e32 v10, 0x3fb8aa3b, v18
	v_sub_f32_e32 v12, v6, v18
	v_add_u32_e32 v1, v1, v7
	v_exp_f32_e32 v10, v10
	v_mul_f32_e32 v11, 0xbfb8aa3b, v18
	v_mul_f32_e32 v12, 0x3fb8aa3b, v12
	v_mad_u64_u32 v[8:9], s[4:5], v1, s3, v[4:5]
	v_exp_f32_e32 v11, v11
	v_exp_f32_e32 v12, v12
	v_lshl_add_u32 v1, v8, 1, s26
	v_cvt_pk_bf16_f32 v8, v14, s0
	v_lshlrev_b32_e32 v9, 16, v52
	ds_write_b16 v1, v13 offset:4096
	ds_write_b16 v1, v8 offset:22528
	v_or_b32_e32 v1, 8, v26
	v_mul_f32_e32 v9, 0x3e000000, v9
	v_add_u32_e32 v8, s38, v1
	v_lshlrev_b32_e32 v13, 16, v51
	v_mul_f32_e32 v9, v9, v10
	v_mul_f32_e32 v14, v11, v13
	v_mul_f32_e32 v12, v12, v13
	v_cvt_pk_bf16_f32 v13, v9, s0
	v_ashrrev_i32_e32 v9, 31, v8
	v_lshl_add_u64 v[8:9], v[8:9], 0, v[132:133]
	v_lshlrev_b64 v[8:9], 7, v[8:9]
	v_or_b32_e32 v8, v8, v0
	v_lshl_add_u64 v[10:11], s[0:1], 0, v[8:9]
; DI float bf2f(bf16_t b) { return __uint_as_float(((unsigned)b) << 16); }
; DI void gla_prep_item(const P& p, int l, int item, unsigned char* smem) {
;     ...
;     for (int ii = 0; ii < 16; ++ii) {
;         const int i = 16 * half + ii, pp = 32 * c + i;
;         const float q = bf2f(qraw[ii]) * 0.125f, k = bf2f(kraw[ii]);
;         const float qt = q * __expf(cum[ii]), kt = k * __expf(-cum[ii]), ko = k * __expf(cl - cum[ii]);
;         QT[((size_t)seq * PT + pp) * 64 + d] = f2bf(qt); KO[((size_t)seq * PT + pp) * 64 + d] = f2bf(ko);
;         sq[(h * 32 + i) * 72 + d] = f2bf(qt); sk[(h * 32 + i) * 72 + d] = f2bf(kt);
	global_store_short v[10:11], v13, off
	v_cvt_pk_bf16_f32 v10, v12, s0
	v_lshl_add_u64 v[8:9], s[36:37], 0, v[8:9]
	global_store_short v[8:9], v10, off
	v_add_u32_e32 v1, v1, v7
	v_mul_f32_e32 v10, 0x3fb8aa3b, v19
	v_sub_f32_e32 v12, v6, v19
	v_mul_lo_u32 v1, v1, s3
	v_exp_f32_e32 v10, v10
	v_mul_f32_e32 v11, 0xbfb8aa3b, v19
	v_mul_f32_e32 v12, 0x3fb8aa3b, v12
	v_or_b32_e32 v1, v1, v4
	v_exp_f32_e32 v11, v11
	v_exp_f32_e32 v12, v12
	v_lshl_add_u32 v1, v1, 1, s26
	v_cvt_pk_bf16_f32 v8, v14, s0
	v_lshlrev_b32_e32 v9, 16, v50
	ds_write_b16 v1, v13 offset:4096
	ds_write_b16 v1, v8 offset:22528
	v_or_b32_e32 v1, 9, v26
	v_mul_f32_e32 v9, 0x3e000000, v9
	v_add_u32_e32 v8, s38, v1
	v_lshlrev_b32_e32 v13, 16, v49
	v_mul_f32_e32 v9, v9, v10
	v_mul_f32_e32 v14, v11, v13
	v_mul_f32_e32 v12, v12, v13
	v_cvt_pk_bf16_f32 v13, v9, s0
	v_ashrrev_i32_e32 v9, 31, v8
	v_lshl_add_u64 v[8:9], v[8:9], 0, v[132:133]
	v_lshlrev_b64 v[8:9], 7, v[8:9]
	v_or_b32_e32 v8, v8, v0
	v_lshl_add_u64 v[10:11], s[0:1], 0, v[8:9]
	global_store_short v[10:11], v13, off
	v_cvt_pk_bf16_f32 v10, v12, s0
	v_lshl_add_u64 v[8:9], s[36:37], 0, v[8:9]
	global_store_short v[8:9], v10, off
	v_mul_f32_e32 v10, 0x3fb8aa3b, v20
	v_sub_f32_e32 v12, v6, v20
	v_add_u32_e32 v1, v1, v7
	v_exp_f32_e32 v10, v10
	v_mul_f32_e32 v11, 0xbfb8aa3b, v20
	v_mul_f32_e32 v12, 0x3fb8aa3b, v12
	v_mad_u64_u32 v[8:9], s[4:5], v1, s3, v[4:5]
	v_exp_f32_e32 v11, v11
	v_exp_f32_e32 v12, v12
	v_lshl_add_u32 v1, v8, 1, s26
	v_cvt_pk_bf16_f32 v8, v14, s0
	v_lshlrev_b32_e32 v9, 16, v48
	ds_write_b16 v1, v13 offset:4096
	ds_write_b16 v1, v8 offset:22528
	v_or_b32_e32 v1, 10, v26
	v_mul_f32_e32 v9, 0x3e000000, v9
	v_add_u32_e32 v8, s38, v1
	v_lshlrev_b32_e32 v13, 16, v47
	v_mul_f32_e32 v9, v9, v10
	v_mul_f32_e32 v14, v11, v13
	v_mul_f32_e32 v12, v12, v13
	v_cvt_pk_bf16_f32 v13, v9, s0
	v_ashrrev_i32_e32 v9, 31, v8
	v_lshl_add_u64 v[8:9], v[8:9], 0, v[132:133]
	v_lshlrev_b64 v[8:9], 7, v[8:9]
	v_or_b32_e32 v8, v8, v0
	v_lshl_add_u64 v[10:11], s[0:1], 0, v[8:9]
	global_store_short v[10:11], v13, off
	v_cvt_pk_bf16_f32 v10, v12, s0
	v_lshl_add_u64 v[8:9], s[36:37], 0, v[8:9]
	global_store_short v[8:9], v10, off
	v_mul_f32_e32 v10, 0x3fb8aa3b, v21
	v_sub_f32_e32 v12, v6, v21
	v_add_u32_e32 v1, v1, v7
	v_exp_f32_e32 v10, v10
	v_mul_f32_e32 v11, 0xbfb8aa3b, v21
	v_mul_f32_e32 v12, 0x3fb8aa3b, v12
	v_mad_u64_u32 v[8:9], s[4:5], v1, s3, v[4:5]
	v_exp_f32_e32 v11, v11
	v_exp_f32_e32 v12, v12
	v_lshl_add_u32 v1, v8, 1, s26
	v_cvt_pk_bf16_f32 v8, v14, s0
	v_lshlrev_b32_e32 v9, 16, v46
	ds_write_b16 v1, v13 offset:4096
	ds_write_b16 v1, v8 offset:22528
	v_or_b32_e32 v1, 11, v26
	v_mul_f32_e32 v9, 0x3e000000, v9
	v_add_u32_e32 v8, s38, v1
	v_lshlrev_b32_e32 v13, 16, v45
	v_mul_f32_e32 v9, v9, v10
	v_mul_f32_e32 v14, v11, v13
	v_mul_f32_e32 v12, v12, v13
	v_cvt_pk_bf16_f32 v13, v9, s0
	v_ashrrev_i32_e32 v9, 31, v8
	v_lshl_add_u64 v[8:9], v[8:9], 0, v[132:133]
	v_lshlrev_b64 v[8:9], 7, v[8:9]
	v_or_b32_e32 v8, v8, v0
	v_lshl_add_u64 v[10:11], s[0:1], 0, v[8:9]
	global_store_short v[10:11], v13, off
	v_cvt_pk_bf16_f32 v10, v12, s0
	v_lshl_add_u64 v[8:9], s[36:37], 0, v[8:9]
	global_store_short v[8:9], v10, off
	v_mul_f32_e32 v10, 0x3fb8aa3b, v22
	v_sub_f32_e32 v12, v6, v22
	v_add_u32_e32 v1, v1, v7
	v_exp_f32_e32 v10, v10
	v_mul_f32_e32 v11, 0xbfb8aa3b, v22
	v_mul_f32_e32 v12, 0x3fb8aa3b, v12
	v_mad_u64_u32 v[8:9], s[4:5], v1, s3, v[4:5]
	v_exp_f32_e32 v11, v11
	v_exp_f32_e32 v12, v12
	v_lshl_add_u32 v1, v8, 1, s26
	v_cvt_pk_bf16_f32 v8, v14, s0
	v_lshlrev_b32_e32 v9, 16, v44
	ds_write_b16 v1, v13 offset:4096
	ds_write_b16 v1, v8 offset:22528
	v_or_b32_e32 v1, 12, v26
	v_mul_f32_e32 v9, 0x3e000000, v9
	v_add_u32_e32 v8, s38, v1
	v_lshlrev_b32_e32 v13, 16, v42
	v_mul_f32_e32 v9, v9, v10
	v_mul_f32_e32 v14, v11, v13
	v_mul_f32_e32 v12, v12, v13
	v_cvt_pk_bf16_f32 v13, v9, s0
	v_ashrrev_i32_e32 v9, 31, v8
	v_lshl_add_u64 v[8:9], v[8:9], 0, v[132:133]
; DI float bf2f(bf16_t b) { return __uint_as_float(((unsigned)b) << 16); }
; DI void gla_prep_item(const P& p, int l, int item, unsigned char* smem) {
;     ...
;     for (int ii = 0; ii < 16; ++ii) {
;         const int i = 16 * half + ii, pp = 32 * c + i;
;         const float q = bf2f(qraw[ii]) * 0.125f, k = bf2f(kraw[ii]);
;         const float qt = q * __expf(cum[ii]), kt = k * __expf(-cum[ii]), ko = k * __expf(cl - cum[ii]);
;         QT[((size_t)seq * PT + pp) * 64 + d] = f2bf(qt); KO[((size_t)seq * PT + pp) * 64 + d] = f2bf(ko);
;         sq[(h * 32 + i) * 72 + d] = f2bf(qt); sk[(h * 32 + i) * 72 + d] = f2bf(kt);
;     }
;     if (half == 0) DC[((size_t)seq * 72 + c) * 64 + d] = __expf(cl);
	v_lshlrev_b64 v[8:9], 7, v[8:9]
	v_or_b32_e32 v8, v8, v0
	v_lshl_add_u64 v[10:11], s[0:1], 0, v[8:9]
	global_store_short v[10:11], v13, off
	v_cvt_pk_bf16_f32 v10, v12, s0
	v_lshl_add_u64 v[8:9], s[36:37], 0, v[8:9]
	global_store_short v[8:9], v10, off
	v_mul_f32_e32 v10, 0x3fb8aa3b, v23
	v_sub_f32_e32 v12, v6, v23
	v_add_u32_e32 v1, v1, v7
	v_exp_f32_e32 v10, v10
	v_mul_f32_e32 v11, 0xbfb8aa3b, v23
	v_mul_f32_e32 v12, 0x3fb8aa3b, v12
	v_mad_u64_u32 v[8:9], s[4:5], v1, s3, v[4:5]
	v_exp_f32_e32 v11, v11
	v_exp_f32_e32 v12, v12
	v_lshl_add_u32 v1, v8, 1, s26
	v_cvt_pk_bf16_f32 v8, v14, s0
	v_lshlrev_b32_e32 v9, 16, v41
	ds_write_b16 v1, v13 offset:4096
	ds_write_b16 v1, v8 offset:22528
	v_or_b32_e32 v1, 13, v26
	v_mul_f32_e32 v9, 0x3e000000, v9
	v_add_u32_e32 v8, s38, v1
	v_lshlrev_b32_e32 v13, 16, v40
	v_mul_f32_e32 v9, v9, v10
	v_mul_f32_e32 v14, v11, v13
	v_mul_f32_e32 v12, v12, v13
	v_cvt_pk_bf16_f32 v13, v9, s0
	v_ashrrev_i32_e32 v9, 31, v8
	v_lshl_add_u64 v[8:9], v[8:9], 0, v[132:133]
	v_lshlrev_b64 v[8:9], 7, v[8:9]
	v_or_b32_e32 v8, v8, v0
	v_lshl_add_u64 v[10:11], s[0:1], 0, v[8:9]
	global_store_short v[10:11], v13, off
	v_cvt_pk_bf16_f32 v10, v12, s0
	v_lshl_add_u64 v[8:9], s[36:37], 0, v[8:9]
	global_store_short v[8:9], v10, off
	v_mul_f32_e32 v10, 0x3fb8aa3b, v2
	v_mul_f32_e32 v11, 0xbfb8aa3b, v2
	v_sub_f32_e32 v2, v6, v2
	v_add_u32_e32 v1, v1, v7
	v_exp_f32_e32 v10, v10
	v_mul_f32_e32 v2, 0x3fb8aa3b, v2
	v_mad_u64_u32 v[8:9], s[4:5], v1, s3, v[4:5]
	v_exp_f32_e32 v11, v11
	v_exp_f32_e32 v2, v2
	v_lshl_add_u32 v1, v8, 1, s26
	v_cvt_pk_bf16_f32 v8, v14, s0
	v_lshlrev_b32_e32 v9, 16, v39
	ds_write_b16 v1, v13 offset:4096
	ds_write_b16 v1, v8 offset:22528
	v_or_b32_e32 v1, 14, v26
	v_mul_f32_e32 v9, 0x3e000000, v9
	v_add_u32_e32 v8, s38, v1
	v_lshlrev_b32_e32 v12, 16, v38
	v_mul_f32_e32 v9, v9, v10
	v_mul_f32_e32 v13, v11, v12
	v_mul_f32_e32 v2, v2, v12
	v_cvt_pk_bf16_f32 v12, v9, s0
	v_ashrrev_i32_e32 v9, 31, v8
	v_lshl_add_u64 v[8:9], v[8:9], 0, v[132:133]
	v_lshlrev_b64 v[8:9], 7, v[8:9]
	v_or_b32_e32 v8, v8, v0
	v_lshl_add_u64 v[10:11], s[0:1], 0, v[8:9]
	v_cvt_pk_bf16_f32 v2, v2, s0
	v_lshl_add_u64 v[8:9], s[36:37], 0, v[8:9]
	v_add_u32_e32 v1, v1, v7
	global_store_short v[8:9], v2, off
	v_mad_u64_u32 v[8:9], s[4:5], v1, s3, v[4:5]
	global_store_short v[10:11], v12, off
	v_mul_f32_e32 v9, 0x3fb8aa3b, v3
	v_mul_f32_e32 v10, 0xbfb8aa3b, v3
	v_sub_f32_e32 v3, v6, v3
	v_mul_f32_e32 v3, 0x3fb8aa3b, v3
	v_exp_f32_e32 v9, v9
	v_exp_f32_e32 v10, v10
	v_exp_f32_e32 v3, v3
	v_lshl_add_u32 v1, v8, 1, s26
	v_cvt_pk_bf16_f32 v2, v13, s0
	ds_write_b16 v1, v12 offset:4096
	ds_write_b16 v1, v2 offset:22528
	v_or_b32_e32 v8, 15, v26
	v_lshlrev_b32_e32 v1, 16, v36
	v_add_u32_e32 v2, s38, v8
	v_mul_f32_e32 v1, 0x3e000000, v1
	v_lshlrev_b32_e32 v11, 16, v35
	v_mul_f32_e32 v1, v1, v9
	v_mul_f32_e32 v9, v10, v11
	v_mul_f32_e32 v10, v3, v11
	v_ashrrev_i32_e32 v3, 31, v2
	v_lshl_add_u64 v[2:3], v[2:3], 0, v[132:133]
	v_lshlrev_b64 v[2:3], 7, v[2:3]
	v_or_b32_e32 v2, v2, v0
	v_cvt_pk_bf16_f32 v11, v1, s0
	v_lshl_add_u64 v[0:1], s[0:1], 0, v[2:3]
	global_store_short v[0:1], v11, off
	v_cvt_pk_bf16_f32 v10, v10, s0
	v_lshl_add_u64 v[0:1], s[36:37], 0, v[2:3]
	global_store_short v[0:1], v10, off
	v_add_u32_e32 v0, v8, v7
	v_mad_u64_u32 v[0:1], s[0:1], v0, s3, v[4:5]
	v_lshl_add_u32 v0, v0, 1, s26
	s_nop 0
	v_cvt_pk_bf16_f32 v1, v9, s0
	ds_write_b16 v0, v11 offset:4096
	ds_write_b16 v0, v1 offset:22528
	s_waitcnt lgkmcnt(0)
	s_and_saveexec_b64 s[0:1], vcc
	s_cbranch_execz .LBB0_264
	v_mul_f32_e32 v0, 0x3fb8aa3b, v6
	v_exp_f32_e32 v2, v0
	v_mul_u32_u24_e32 v0, 0x48, v5
	v_add_lshl_u32 v132, v0, s21, 8
	v_lshl_add_u64 v[0:1], s[42:43], 0, v[132:133]
	v_lshlrev_b32_e32 v132, 2, v4
	v_lshl_add_u64 v[0:1], v[0:1], 0, v[132:133]
	v_add_co_u32_e32 v0, vcc, 0x12cbc000, v0
	s_nop 1
	v_addc_co_u32_e32 v1, vcc, 0, v1, vcc
	global_store_dword v[0:1], v2, off
